# phase-0 row loop compacted to one 2-row batch per iteration (shorter once-executed code: instruction fetch of cold code costs ~0.75 us/KB)
# speedup vs baseline: 1.0711x; 1.0060x over previous
.Lp0_nokm:
	v_lshrrev_b32_e32 v0, 2, v198
	s_mov_b32 s20, 0xc040
	v_mul_lo_u32 v0, v0, s20
	v_and_b32_e32 v1, 3, v198
	v_lshl_add_u32 v0, v1, 4, v0
	s_add_u32 s18, s10, 0x4000
	s_addc_u32 s19, s11, 0
	global_load_dwordx4 v[4:7], v0, s[18:19]
	s_add_u32 s18, s18, 0x602000
	s_addc_u32 s19, s19, 0
	global_load_dwordx4 v[8:11], v0, s[18:19]
	s_add_u32 s18, s18, 0x602000
	s_addc_u32 s19, s19, 0
	global_load_dwordx4 v[12:15], v0, s[18:19]
	s_add_u32 s18, s18, 0x602000
	s_addc_u32 s19, s19, 0
	global_load_dwordx4 v[16:19], v0, s[18:19]
	s_add_u32 s18, s18, 0x602000
	s_addc_u32 s19, s19, 0
	global_load_dwordx4 v[20:23], v0, s[18:19]
	s_add_u32 s18, s18, 0x602000
	s_addc_u32 s19, s19, 0
	global_load_dwordx4 v[24:27], v0, s[18:19]
	s_add_u32 s18, s18, 0x602000
	s_addc_u32 s19, s19, 0
	global_load_dwordx4 v[28:31], v0, s[18:19]
	s_add_u32 s18, s18, 0x602000
	s_addc_u32 s19, s19, 0
	global_load_dwordx4 v[32:35], v0, s[18:19]
	s_add_u32 s18, s18, 0x602000
	s_addc_u32 s19, s19, 0
	global_load_dwordx4 v[36:39], v0, s[18:19]
	s_add_u32 s18, s18, 0x602000
	s_addc_u32 s19, s19, 0
	global_load_dwordx4 v[40:43], v0, s[18:19]
	s_add_u32 s18, s18, 0x602000
	s_addc_u32 s19, s19, 0
	global_load_dwordx4 v[44:47], v0, s[18:19]
	s_add_u32 s18, s18, 0x602000
	s_addc_u32 s19, s19, 0
	global_load_dwordx4 v[48:51], v0, s[18:19]
	s_add_u32 s18, s18, 0x602000
	s_addc_u32 s19, s19, 0
	global_load_dwordx4 v[52:55], v0, s[18:19]
	s_add_u32 s18, s18, 0x602000
	s_addc_u32 s19, s19, 0
	global_load_dwordx4 v[56:59], v0, s[18:19]
	s_add_u32 s18, s18, 0x602000
	s_addc_u32 s19, s19, 0
	global_load_dwordx4 v[60:63], v0, s[18:19]
	s_add_u32 s18, s18, 0x602000
	s_addc_u32 s19, s19, 0
	global_load_dwordx4 v[64:67], v0, s[18:19]
	s_add_u32 s32, s8, 0x1000
	s_addc_u32 s33, s9, 0
	global_load_dwordx4 v[200:203], v166, s[8:9] offset:0
	global_load_dwordx4 v[204:207], v166, s[8:9] offset:1024
	global_load_dwordx4 v[208:211], v166, s[8:9] offset:2048
	global_load_dwordx4 v[212:215], v166, s[8:9] offset:3072
	global_load_dwordx4 v[216:219], v166, s[32:33] offset:0
	global_load_dwordx4 v[220:223], v166, s[32:33] offset:1024
	global_load_dwordx4 v[224:227], v166, s[32:33] offset:2048
	global_load_dwordx4 v[228:231], v166, s[32:33] offset:3072
	v_bfe_u32 v2, v198, 2, 2
	v_lshrrev_b32_e32 v3, 4, v198
	v_lshl_add_u32 v2, v2, 6, v3
	v_lshlrev_b32_e32 v2, 6, v2
	v_add_u32_e32 v3, v1, v196
	v_and_b32_e32 v3, 3, v3
	v_lshl_add_u32 v2, v3, 4, v2
	s_waitcnt vmcnt(23)
	ds_write_b128 v2, v[4:7] offset:0
	s_waitcnt vmcnt(22)
	ds_write_b128 v2, v[8:11] offset:2048
	s_waitcnt vmcnt(21)
	ds_write_b128 v2, v[12:15] offset:16384
	s_waitcnt vmcnt(20)
	ds_write_b128 v2, v[16:19] offset:18432
	s_waitcnt vmcnt(19)
	ds_write_b128 v2, v[20:23] offset:32768
	s_waitcnt vmcnt(18)
	ds_write_b128 v2, v[24:27] offset:34816
	s_waitcnt vmcnt(17)
	ds_write_b128 v2, v[28:31] offset:49152
	s_waitcnt vmcnt(16)
	ds_write_b128 v2, v[32:35] offset:51200
	s_waitcnt vmcnt(15)
	v_add_u32_e32 v3, 0x10000, v2
	ds_write_b128 v3, v[36:39] offset:0
	s_waitcnt vmcnt(14)
	ds_write_b128 v3, v[40:43] offset:2048
	s_waitcnt vmcnt(13)
	ds_write_b128 v3, v[44:47] offset:16384
	s_waitcnt vmcnt(12)
	ds_write_b128 v3, v[48:51] offset:18432
	s_waitcnt vmcnt(11)
	ds_write_b128 v3, v[52:55] offset:32768
	s_waitcnt vmcnt(10)
	ds_write_b128 v3, v[56:59] offset:34816
	s_waitcnt vmcnt(9)
	ds_write_b128 v3, v[60:63] offset:49152
	s_waitcnt vmcnt(8)
	ds_write_b128 v3, v[64:67] offset:51200
	v_lshrrev_b32_e32 v0, 2, v197
	v_add_u32_e32 v1, 0, v0
	v_and_b32_e32 v1, 3, v1
	v_lshlrev_b32_e32 v1, 4, v1
	v_lshl_add_u32 v244, v197, 6, v1
	v_add_u32_e32 v248, 0x10000, v244
	v_add_u32_e32 v1, 1, v0
	v_and_b32_e32 v1, 3, v1
	v_lshlrev_b32_e32 v1, 4, v1
	v_lshl_add_u32 v245, v197, 6, v1
	v_add_u32_e32 v249, 0x10000, v245
	v_add_u32_e32 v1, 2, v0
	v_and_b32_e32 v1, 3, v1
	v_lshlrev_b32_e32 v1, 4, v1
	v_lshl_add_u32 v246, v197, 6, v1
	v_add_u32_e32 v250, 0x10000, v246
	v_add_u32_e32 v1, 3, v0
	v_and_b32_e32 v1, 3, v1
	v_lshlrev_b32_e32 v1, 4, v1
	v_lshl_add_u32 v247, v197, 6, v1
	v_add_u32_e32 v251, 0x10000, v247
	v_and_b32_e32 v0, 32, v197
	v_cmp_ne_u32_e64 s[24:25], 0, v0
	v_and_b32_e32 v0, 16, v197
	v_cmp_ne_u32_e64 s[26:27], 0, v0
	v_and_b32_e32 v0, 8, v197
	v_cmp_ne_u32_e64 s[28:29], 0, v0
	v_and_b32_e32 v0, 4, v197
	v_cmp_ne_u32_e64 s[30:31], 0, v0
	v_and_b32_e32 v0, 2, v197
	v_cmp_ne_u32_e64 s[34:35], 0, v0
	v_bfe_u32 v0, v197, 1, 3
	v_lshlrev_b32_e32 v0, 2, v0
	global_load_dword v237, v0, s[36:37]
	global_load_dword v195, v0, s[38:39]
	s_waitcnt vmcnt(0) lgkmcnt(0)
	v_mul_f32_e32 v237, 0x3fb8aa3b, v237
	v_exp_f32_e32 v237, v237
	s_mov_b32 s20, 0x3a000000
	s_barrier
	v_readfirstlane_b32 s18, v196
	s_lshl_b32 s16, s96, 6
	s_lshl_b32 s18, s18, 3
	s_add_u32 s16, s16, s18
	s_lshl_b32 s18, s16, 13
	s_add_u32 s22, s4, s18
	s_addc_u32 s23, s5, 0
	s_add_u32 s32, s22, 0x1000
	s_addc_u32 s33, s23, 0
	global_load_dwordx4 v[64:67], v166, s[22:23] offset:0
	global_load_dwordx4 v[68:71], v166, s[22:23] offset:1024
	global_load_dwordx4 v[72:75], v166, s[22:23] offset:2048
	global_load_dwordx4 v[76:79], v166, s[22:23] offset:3072
	global_load_dwordx4 v[80:83], v166, s[32:33] offset:0
	global_load_dwordx4 v[84:87], v166, s[32:33] offset:1024
	global_load_dwordx4 v[88:91], v166, s[32:33] offset:2048
	global_load_dwordx4 v[92:95], v166, s[32:33] offset:3072
	s_add_u32 s22, s22, 0x2000
	s_addc_u32 s23, s23, 0
	s_add_u32 s32, s22, 0x1000
	s_addc_u32 s33, s23, 0
	global_load_dwordx4 v[96:99], v166, s[22:23] offset:0
	global_load_dwordx4 v[100:103], v166, s[22:23] offset:1024
	global_load_dwordx4 v[104:107], v166, s[22:23] offset:2048
	global_load_dwordx4 v[108:111], v166, s[22:23] offset:3072
	global_load_dwordx4 v[112:115], v166, s[32:33] offset:0
	global_load_dwordx4 v[116:119], v166, s[32:33] offset:1024
	global_load_dwordx4 v[120:123], v166, s[32:33] offset:2048
	global_load_dwordx4 v[124:127], v166, s[32:33] offset:3072
	s_mov_b32 s17, 0
.Lp0_loop:
	s_cmp_eq_u32 s17, 0
	s_cbranch_scc1 .Lp0_first
	s_waitcnt vmcnt(18)
	s_branch .Lp0_cp

.Lp0_cp:
	v_mov_b32_e32 v0, v64
	v_mov_b32_e32 v1, v65
	v_mov_b32_e32 v2, v66
	v_mov_b32_e32 v3, v67
	v_mov_b32_e32 v4, v68
	v_mov_b32_e32 v5, v69
	v_mov_b32_e32 v6, v70
	v_mov_b32_e32 v7, v71
	v_mov_b32_e32 v8, v72
	v_mov_b32_e32 v9, v73
	v_mov_b32_e32 v10, v74
	v_mov_b32_e32 v11, v75
	v_mov_b32_e32 v12, v76
	v_mov_b32_e32 v13, v77
	v_mov_b32_e32 v14, v78
	v_mov_b32_e32 v15, v79
	v_mov_b32_e32 v16, v80
	v_mov_b32_e32 v17, v81
	v_mov_b32_e32 v18, v82
	v_mov_b32_e32 v19, v83
	v_mov_b32_e32 v20, v84
	v_mov_b32_e32 v21, v85
	v_mov_b32_e32 v22, v86
	v_mov_b32_e32 v23, v87
	v_mov_b32_e32 v24, v88
	v_mov_b32_e32 v25, v89
	v_mov_b32_e32 v26, v90
	v_mov_b32_e32 v27, v91
	v_mov_b32_e32 v28, v92
	v_mov_b32_e32 v29, v93
	v_mov_b32_e32 v30, v94
	v_mov_b32_e32 v31, v95
	v_mov_b32_e32 v32, v96
	v_mov_b32_e32 v33, v97
	v_mov_b32_e32 v34, v98
	v_mov_b32_e32 v35, v99
	v_mov_b32_e32 v36, v100
	v_mov_b32_e32 v37, v101
	v_mov_b32_e32 v38, v102
	v_mov_b32_e32 v39, v103
	v_mov_b32_e32 v40, v104
	v_mov_b32_e32 v41, v105
	v_mov_b32_e32 v42, v106
	v_mov_b32_e32 v43, v107
	v_mov_b32_e32 v44, v108
	v_mov_b32_e32 v45, v109
	v_mov_b32_e32 v46, v110
	v_mov_b32_e32 v47, v111
	v_mov_b32_e32 v48, v112
	v_mov_b32_e32 v49, v113
	v_mov_b32_e32 v50, v114
	v_mov_b32_e32 v51, v115
	v_mov_b32_e32 v52, v116
	v_mov_b32_e32 v53, v117
	v_mov_b32_e32 v54, v118
	v_mov_b32_e32 v55, v119
	v_mov_b32_e32 v56, v120
	v_mov_b32_e32 v57, v121
	v_mov_b32_e32 v58, v122
	v_mov_b32_e32 v59, v123
	v_mov_b32_e32 v60, v124
	v_mov_b32_e32 v61, v125
	v_mov_b32_e32 v62, v126
	v_mov_b32_e32 v63, v127
	s_cmp_ge_u32 s17, 3
	s_cbranch_scc1 .Lp0_nopf
	s_add_u32 s16, s16, 2
	s_lshl_b32 s18, s16, 13
	s_add_u32 s22, s4, s18
	s_addc_u32 s23, s5, 0
	s_add_u32 s32, s22, 0x1000
	s_addc_u32 s33, s23, 0
	global_load_dwordx4 v[64:67], v166, s[22:23] offset:0
	global_load_dwordx4 v[68:71], v166, s[22:23] offset:1024
	global_load_dwordx4 v[72:75], v166, s[22:23] offset:2048
	global_load_dwordx4 v[76:79], v166, s[22:23] offset:3072
	global_load_dwordx4 v[80:83], v166, s[32:33] offset:0
	global_load_dwordx4 v[84:87], v166, s[32:33] offset:1024
	global_load_dwordx4 v[88:91], v166, s[32:33] offset:2048
	global_load_dwordx4 v[92:95], v166, s[32:33] offset:3072
	s_add_u32 s22, s22, 0x2000
	s_addc_u32 s23, s23, 0
	s_add_u32 s32, s22, 0x1000
	s_addc_u32 s33, s23, 0
	global_load_dwordx4 v[96:99], v166, s[22:23] offset:0
	global_load_dwordx4 v[100:103], v166, s[22:23] offset:1024
	global_load_dwordx4 v[104:107], v166, s[22:23] offset:2048
	global_load_dwordx4 v[108:111], v166, s[22:23] offset:3072
	global_load_dwordx4 v[112:115], v166, s[32:33] offset:0
	global_load_dwordx4 v[116:119], v166, s[32:33] offset:1024
	global_load_dwordx4 v[120:123], v166, s[32:33] offset:2048
	global_load_dwordx4 v[124:127], v166, s[32:33] offset:3072
	s_sub_u32 s16, s16, 2
.Lp0_nopf:
	v_mov_b32_e32 v128, 0
	v_mov_b32_e32 v129, 0
	v_mov_b32_e32 v130, 0
	v_mov_b32_e32 v131, 0
	v_mov_b32_e32 v132, 0
	v_mov_b32_e32 v133, 0
	v_mov_b32_e32 v134, 0
	v_mov_b32_e32 v135, 0
	v_mov_b32_e32 v136, 0
	v_mov_b32_e32 v137, 0
	v_mov_b32_e32 v138, 0
	v_mov_b32_e32 v139, 0
	v_mov_b32_e32 v140, 0
	v_mov_b32_e32 v141, 0
	v_mov_b32_e32 v142, 0
	v_mov_b32_e32 v143, 0
	v_mov_b32_e32 v254, 0
	v_mov_b32_e32 v144, 0
	v_mov_b32_e32 v145, 0
	v_mov_b32_e32 v146, 0
	v_mov_b32_e32 v147, 0
	v_mov_b32_e32 v148, 0
	v_mov_b32_e32 v149, 0
	v_mov_b32_e32 v150, 0
	v_mov_b32_e32 v151, 0
	v_mov_b32_e32 v152, 0
	v_mov_b32_e32 v153, 0
	v_mov_b32_e32 v154, 0
	v_mov_b32_e32 v155, 0
	v_mov_b32_e32 v156, 0
	v_mov_b32_e32 v157, 0
	v_mov_b32_e32 v158, 0
	v_mov_b32_e32 v159, 0
	v_mov_b32_e32 v255, 0
	ds_read_b128 v[168:171], v244 offset:0
	ds_read_b128 v[172:175], v245 offset:0
	ds_read_b128 v[176:179], v246 offset:0
	ds_read_b128 v[180:183], v247 offset:0
	ds_read_b128 v[184:187], v244 offset:4096
	ds_read_b128 v[188:191], v245 offset:4096
	ds_read_b128 v[232:235], v246 offset:4096
	ds_read_b128 v[240:243], v247 offset:4096
	v_mul_f32_e32 v252, v0, v200
	v_fmac_f32_e32 v254, v0, v0
	v_mul_f32_e32 v253, v32, v200
	v_fmac_f32_e32 v255, v32, v32
	s_waitcnt lgkmcnt(7)
	v_fmac_f32_e32 v128, v252, v168
	v_fmac_f32_e32 v144, v253, v168
	v_fmac_f32_e32 v129, v252, v169
	v_fmac_f32_e32 v145, v253, v169
	v_fmac_f32_e32 v130, v252, v170
	v_fmac_f32_e32 v146, v253, v170
	v_fmac_f32_e32 v131, v252, v171
	v_fmac_f32_e32 v147, v253, v171
	s_waitcnt lgkmcnt(6)
	v_fmac_f32_e32 v132, v252, v172
	v_fmac_f32_e32 v148, v253, v172
	v_fmac_f32_e32 v133, v252, v173
	v_fmac_f32_e32 v149, v253, v173
	v_fmac_f32_e32 v134, v252, v174
	v_fmac_f32_e32 v150, v253, v174
	v_fmac_f32_e32 v135, v252, v175
	v_fmac_f32_e32 v151, v253, v175
	s_waitcnt lgkmcnt(5)
	v_fmac_f32_e32 v136, v252, v176
	v_fmac_f32_e32 v152, v253, v176
	v_fmac_f32_e32 v137, v252, v177
	v_fmac_f32_e32 v153, v253, v177
	v_fmac_f32_e32 v138, v252, v178
	v_fmac_f32_e32 v154, v253, v178
	v_fmac_f32_e32 v139, v252, v179
	v_fmac_f32_e32 v155, v253, v179
	s_waitcnt lgkmcnt(4)
	v_fmac_f32_e32 v140, v252, v180
	v_fmac_f32_e32 v156, v253, v180
	v_fmac_f32_e32 v141, v252, v181
	v_fmac_f32_e32 v157, v253, v181
	v_fmac_f32_e32 v142, v252, v182
	v_fmac_f32_e32 v158, v253, v182
	v_fmac_f32_e32 v143, v252, v183
	v_fmac_f32_e32 v159, v253, v183
	ds_read_b128 v[168:171], v244 offset:8192
	ds_read_b128 v[172:175], v245 offset:8192
	ds_read_b128 v[176:179], v246 offset:8192
	ds_read_b128 v[180:183], v247 offset:8192
	v_mul_f32_e32 v252, v1, v201
	v_fmac_f32_e32 v254, v1, v1
	v_mul_f32_e32 v253, v33, v201
	v_fmac_f32_e32 v255, v33, v33
	s_waitcnt lgkmcnt(7)
	v_fmac_f32_e32 v128, v252, v184
	v_fmac_f32_e32 v144, v253, v184
	v_fmac_f32_e32 v129, v252, v185
	v_fmac_f32_e32 v145, v253, v185
	v_fmac_f32_e32 v130, v252, v186
	v_fmac_f32_e32 v146, v253, v186
	v_fmac_f32_e32 v131, v252, v187
	v_fmac_f32_e32 v147, v253, v187
	s_waitcnt lgkmcnt(6)
	v_fmac_f32_e32 v132, v252, v188
	v_fmac_f32_e32 v148, v253, v188
	v_fmac_f32_e32 v133, v252, v189
	v_fmac_f32_e32 v149, v253, v189
	v_fmac_f32_e32 v134, v252, v190
	v_fmac_f32_e32 v150, v253, v190
	v_fmac_f32_e32 v135, v252, v191
	v_fmac_f32_e32 v151, v253, v191
	s_waitcnt lgkmcnt(5)
	v_fmac_f32_e32 v136, v252, v232
	v_fmac_f32_e32 v152, v253, v232
	v_fmac_f32_e32 v137, v252, v233
	v_fmac_f32_e32 v153, v253, v233
	v_fmac_f32_e32 v138, v252, v234
	v_fmac_f32_e32 v154, v253, v234
	v_fmac_f32_e32 v139, v252, v235
	v_fmac_f32_e32 v155, v253, v235
	s_waitcnt lgkmcnt(4)
	v_fmac_f32_e32 v140, v252, v240
	v_fmac_f32_e32 v156, v253, v240
	v_fmac_f32_e32 v141, v252, v241
	v_fmac_f32_e32 v157, v253, v241
	v_fmac_f32_e32 v142, v252, v242
	v_fmac_f32_e32 v158, v253, v242
	v_fmac_f32_e32 v143, v252, v243
	v_fmac_f32_e32 v159, v253, v243
	ds_read_b128 v[184:187], v244 offset:12288
	ds_read_b128 v[188:191], v245 offset:12288
	ds_read_b128 v[232:235], v246 offset:12288
	ds_read_b128 v[240:243], v247 offset:12288
	v_mul_f32_e32 v252, v2, v202
	v_fmac_f32_e32 v254, v2, v2
	v_mul_f32_e32 v253, v34, v202
	v_fmac_f32_e32 v255, v34, v34
	s_waitcnt lgkmcnt(7)
	v_fmac_f32_e32 v128, v252, v168
	v_fmac_f32_e32 v144, v253, v168
	v_fmac_f32_e32 v129, v252, v169
	v_fmac_f32_e32 v145, v253, v169
	v_fmac_f32_e32 v130, v252, v170
	v_fmac_f32_e32 v146, v253, v170
	v_fmac_f32_e32 v131, v252, v171
	v_fmac_f32_e32 v147, v253, v171
	s_waitcnt lgkmcnt(6)
	v_fmac_f32_e32 v132, v252, v172
	v_fmac_f32_e32 v148, v253, v172
	v_fmac_f32_e32 v133, v252, v173
	v_fmac_f32_e32 v149, v253, v173
	v_fmac_f32_e32 v134, v252, v174
	v_fmac_f32_e32 v150, v253, v174
	v_fmac_f32_e32 v135, v252, v175
	v_fmac_f32_e32 v151, v253, v175
	s_waitcnt lgkmcnt(5)
	v_fmac_f32_e32 v136, v252, v176
	v_fmac_f32_e32 v152, v253, v176
	v_fmac_f32_e32 v137, v252, v177
	v_fmac_f32_e32 v153, v253, v177
	v_fmac_f32_e32 v138, v252, v178
	v_fmac_f32_e32 v154, v253, v178
	v_fmac_f32_e32 v139, v252, v179
	v_fmac_f32_e32 v155, v253, v179
	s_waitcnt lgkmcnt(4)
	v_fmac_f32_e32 v140, v252, v180
	v_fmac_f32_e32 v156, v253, v180
	v_fmac_f32_e32 v141, v252, v181
	v_fmac_f32_e32 v157, v253, v181
	v_fmac_f32_e32 v142, v252, v182
	v_fmac_f32_e32 v158, v253, v182
	v_fmac_f32_e32 v143, v252, v183
	v_fmac_f32_e32 v159, v253, v183
	ds_read_b128 v[168:171], v244 offset:16384
	ds_read_b128 v[172:175], v245 offset:16384
	ds_read_b128 v[176:179], v246 offset:16384
	ds_read_b128 v[180:183], v247 offset:16384
	v_mul_f32_e32 v252, v3, v203
	v_fmac_f32_e32 v254, v3, v3
	v_mul_f32_e32 v253, v35, v203
	v_fmac_f32_e32 v255, v35, v35
	s_waitcnt lgkmcnt(7)
	v_fmac_f32_e32 v128, v252, v184
	v_fmac_f32_e32 v144, v253, v184
	v_fmac_f32_e32 v129, v252, v185
	v_fmac_f32_e32 v145, v253, v185
	v_fmac_f32_e32 v130, v252, v186
	v_fmac_f32_e32 v146, v253, v186
	v_fmac_f32_e32 v131, v252, v187
	v_fmac_f32_e32 v147, v253, v187
	s_waitcnt lgkmcnt(6)
	v_fmac_f32_e32 v132, v252, v188
	v_fmac_f32_e32 v148, v253, v188
	v_fmac_f32_e32 v133, v252, v189
	v_fmac_f32_e32 v149, v253, v189
	v_fmac_f32_e32 v134, v252, v190
	v_fmac_f32_e32 v150, v253, v190
	v_fmac_f32_e32 v135, v252, v191
	v_fmac_f32_e32 v151, v253, v191
	s_waitcnt lgkmcnt(5)
	v_fmac_f32_e32 v136, v252, v232
	v_fmac_f32_e32 v152, v253, v232
	v_fmac_f32_e32 v137, v252, v233
	v_fmac_f32_e32 v153, v253, v233
	v_fmac_f32_e32 v138, v252, v234
	v_fmac_f32_e32 v154, v253, v234
	v_fmac_f32_e32 v139, v252, v235
	v_fmac_f32_e32 v155, v253, v235
	s_waitcnt lgkmcnt(4)
	v_fmac_f32_e32 v140, v252, v240
	v_fmac_f32_e32 v156, v253, v240
	v_fmac_f32_e32 v141, v252, v241
	v_fmac_f32_e32 v157, v253, v241
	v_fmac_f32_e32 v142, v252, v242
	v_fmac_f32_e32 v158, v253, v242
	v_fmac_f32_e32 v143, v252, v243
	v_fmac_f32_e32 v159, v253, v243
	ds_read_b128 v[184:187], v244 offset:20480
	ds_read_b128 v[188:191], v245 offset:20480
	ds_read_b128 v[232:235], v246 offset:20480
	ds_read_b128 v[240:243], v247 offset:20480
	v_mul_f32_e32 v252, v4, v204
	v_fmac_f32_e32 v254, v4, v4
	v_mul_f32_e32 v253, v36, v204
	v_fmac_f32_e32 v255, v36, v36
	s_waitcnt lgkmcnt(7)
	v_fmac_f32_e32 v128, v252, v168
	v_fmac_f32_e32 v144, v253, v168
	v_fmac_f32_e32 v129, v252, v169
	v_fmac_f32_e32 v145, v253, v169
	v_fmac_f32_e32 v130, v252, v170
	v_fmac_f32_e32 v146, v253, v170
	v_fmac_f32_e32 v131, v252, v171
	v_fmac_f32_e32 v147, v253, v171
	s_waitcnt lgkmcnt(6)
	v_fmac_f32_e32 v132, v252, v172
	v_fmac_f32_e32 v148, v253, v172
	v_fmac_f32_e32 v133, v252, v173
	v_fmac_f32_e32 v149, v253, v173
	v_fmac_f32_e32 v134, v252, v174
	v_fmac_f32_e32 v150, v253, v174
	v_fmac_f32_e32 v135, v252, v175
	v_fmac_f32_e32 v151, v253, v175
	s_waitcnt lgkmcnt(5)
	v_fmac_f32_e32 v136, v252, v176
	v_fmac_f32_e32 v152, v253, v176
	v_fmac_f32_e32 v137, v252, v177
	v_fmac_f32_e32 v153, v253, v177
	v_fmac_f32_e32 v138, v252, v178
	v_fmac_f32_e32 v154, v253, v178
	v_fmac_f32_e32 v139, v252, v179
	v_fmac_f32_e32 v155, v253, v179
	s_waitcnt lgkmcnt(4)
	v_fmac_f32_e32 v140, v252, v180
	v_fmac_f32_e32 v156, v253, v180
	v_fmac_f32_e32 v141, v252, v181
	v_fmac_f32_e32 v157, v253, v181
	v_fmac_f32_e32 v142, v252, v182
	v_fmac_f32_e32 v158, v253, v182
	v_fmac_f32_e32 v143, v252, v183
	v_fmac_f32_e32 v159, v253, v183
	ds_read_b128 v[168:171], v244 offset:24576
	ds_read_b128 v[172:175], v245 offset:24576
	ds_read_b128 v[176:179], v246 offset:24576
	ds_read_b128 v[180:183], v247 offset:24576
	v_mul_f32_e32 v252, v5, v205
	v_fmac_f32_e32 v254, v5, v5
	v_mul_f32_e32 v253, v37, v205
	v_fmac_f32_e32 v255, v37, v37
	s_waitcnt lgkmcnt(7)
	v_fmac_f32_e32 v128, v252, v184
	v_fmac_f32_e32 v144, v253, v184
	v_fmac_f32_e32 v129, v252, v185
	v_fmac_f32_e32 v145, v253, v185
	v_fmac_f32_e32 v130, v252, v186
	v_fmac_f32_e32 v146, v253, v186
	v_fmac_f32_e32 v131, v252, v187
	v_fmac_f32_e32 v147, v253, v187
	s_waitcnt lgkmcnt(6)
	v_fmac_f32_e32 v132, v252, v188
	v_fmac_f32_e32 v148, v253, v188
	v_fmac_f32_e32 v133, v252, v189
	v_fmac_f32_e32 v149, v253, v189
	v_fmac_f32_e32 v134, v252, v190
	v_fmac_f32_e32 v150, v253, v190
	v_fmac_f32_e32 v135, v252, v191
	v_fmac_f32_e32 v151, v253, v191
	s_waitcnt lgkmcnt(5)
	v_fmac_f32_e32 v136, v252, v232
	v_fmac_f32_e32 v152, v253, v232
	v_fmac_f32_e32 v137, v252, v233
	v_fmac_f32_e32 v153, v253, v233
	v_fmac_f32_e32 v138, v252, v234
	v_fmac_f32_e32 v154, v253, v234
	v_fmac_f32_e32 v139, v252, v235
	v_fmac_f32_e32 v155, v253, v235
	s_waitcnt lgkmcnt(4)
	v_fmac_f32_e32 v140, v252, v240
	v_fmac_f32_e32 v156, v253, v240
	v_fmac_f32_e32 v141, v252, v241
	v_fmac_f32_e32 v157, v253, v241
	v_fmac_f32_e32 v142, v252, v242
	v_fmac_f32_e32 v158, v253, v242
	v_fmac_f32_e32 v143, v252, v243
	v_fmac_f32_e32 v159, v253, v243
	ds_read_b128 v[184:187], v244 offset:28672
	ds_read_b128 v[188:191], v245 offset:28672
	ds_read_b128 v[232:235], v246 offset:28672
	ds_read_b128 v[240:243], v247 offset:28672
	v_mul_f32_e32 v252, v6, v206
	v_fmac_f32_e32 v254, v6, v6
	v_mul_f32_e32 v253, v38, v206
	v_fmac_f32_e32 v255, v38, v38
	s_waitcnt lgkmcnt(7)
	v_fmac_f32_e32 v128, v252, v168
	v_fmac_f32_e32 v144, v253, v168
	v_fmac_f32_e32 v129, v252, v169
	v_fmac_f32_e32 v145, v253, v169
	v_fmac_f32_e32 v130, v252, v170
	v_fmac_f32_e32 v146, v253, v170
	v_fmac_f32_e32 v131, v252, v171
	v_fmac_f32_e32 v147, v253, v171
	s_waitcnt lgkmcnt(6)
	v_fmac_f32_e32 v132, v252, v172
	v_fmac_f32_e32 v148, v253, v172
	v_fmac_f32_e32 v133, v252, v173
	v_fmac_f32_e32 v149, v253, v173
	v_fmac_f32_e32 v134, v252, v174
	v_fmac_f32_e32 v150, v253, v174
	v_fmac_f32_e32 v135, v252, v175
	v_fmac_f32_e32 v151, v253, v175
	s_waitcnt lgkmcnt(5)
	v_fmac_f32_e32 v136, v252, v176
	v_fmac_f32_e32 v152, v253, v176
	v_fmac_f32_e32 v137, v252, v177
	v_fmac_f32_e32 v153, v253, v177
	v_fmac_f32_e32 v138, v252, v178
	v_fmac_f32_e32 v154, v253, v178
	v_fmac_f32_e32 v139, v252, v179
	v_fmac_f32_e32 v155, v253, v179
	s_waitcnt lgkmcnt(4)
	v_fmac_f32_e32 v140, v252, v180
	v_fmac_f32_e32 v156, v253, v180
	v_fmac_f32_e32 v141, v252, v181
	v_fmac_f32_e32 v157, v253, v181
	v_fmac_f32_e32 v142, v252, v182
	v_fmac_f32_e32 v158, v253, v182
	v_fmac_f32_e32 v143, v252, v183
	v_fmac_f32_e32 v159, v253, v183
	ds_read_b128 v[168:171], v244 offset:32768
	ds_read_b128 v[172:175], v245 offset:32768
	ds_read_b128 v[176:179], v246 offset:32768
	ds_read_b128 v[180:183], v247 offset:32768
	v_mul_f32_e32 v252, v7, v207
	v_fmac_f32_e32 v254, v7, v7
	v_mul_f32_e32 v253, v39, v207
	v_fmac_f32_e32 v255, v39, v39
	s_waitcnt lgkmcnt(7)
	v_fmac_f32_e32 v128, v252, v184
	v_fmac_f32_e32 v144, v253, v184
	v_fmac_f32_e32 v129, v252, v185
	v_fmac_f32_e32 v145, v253, v185
	v_fmac_f32_e32 v130, v252, v186
	v_fmac_f32_e32 v146, v253, v186
	v_fmac_f32_e32 v131, v252, v187
	v_fmac_f32_e32 v147, v253, v187
	s_waitcnt lgkmcnt(6)
	v_fmac_f32_e32 v132, v252, v188
	v_fmac_f32_e32 v148, v253, v188
	v_fmac_f32_e32 v133, v252, v189
	v_fmac_f32_e32 v149, v253, v189
	v_fmac_f32_e32 v134, v252, v190
	v_fmac_f32_e32 v150, v253, v190
	v_fmac_f32_e32 v135, v252, v191
	v_fmac_f32_e32 v151, v253, v191
	s_waitcnt lgkmcnt(5)
	v_fmac_f32_e32 v136, v252, v232
	v_fmac_f32_e32 v152, v253, v232
	v_fmac_f32_e32 v137, v252, v233
	v_fmac_f32_e32 v153, v253, v233
	v_fmac_f32_e32 v138, v252, v234
	v_fmac_f32_e32 v154, v253, v234
	v_fmac_f32_e32 v139, v252, v235
	v_fmac_f32_e32 v155, v253, v235
	s_waitcnt lgkmcnt(4)
	v_fmac_f32_e32 v140, v252, v240
	v_fmac_f32_e32 v156, v253, v240
	v_fmac_f32_e32 v141, v252, v241
	v_fmac_f32_e32 v157, v253, v241
	v_fmac_f32_e32 v142, v252, v242
	v_fmac_f32_e32 v158, v253, v242
	v_fmac_f32_e32 v143, v252, v243
	v_fmac_f32_e32 v159, v253, v243
	ds_read_b128 v[184:187], v244 offset:36864
	ds_read_b128 v[188:191], v245 offset:36864
	ds_read_b128 v[232:235], v246 offset:36864
	ds_read_b128 v[240:243], v247 offset:36864
	v_mul_f32_e32 v252, v8, v208
	v_fmac_f32_e32 v254, v8, v8
	v_mul_f32_e32 v253, v40, v208
	v_fmac_f32_e32 v255, v40, v40
	s_waitcnt lgkmcnt(7)
	v_fmac_f32_e32 v128, v252, v168
	v_fmac_f32_e32 v144, v253, v168
	v_fmac_f32_e32 v129, v252, v169
	v_fmac_f32_e32 v145, v253, v169
	v_fmac_f32_e32 v130, v252, v170
	v_fmac_f32_e32 v146, v253, v170
	v_fmac_f32_e32 v131, v252, v171
	v_fmac_f32_e32 v147, v253, v171
	s_waitcnt lgkmcnt(6)
	v_fmac_f32_e32 v132, v252, v172
	v_fmac_f32_e32 v148, v253, v172
	v_fmac_f32_e32 v133, v252, v173
	v_fmac_f32_e32 v149, v253, v173
	v_fmac_f32_e32 v134, v252, v174
	v_fmac_f32_e32 v150, v253, v174
	v_fmac_f32_e32 v135, v252, v175
	v_fmac_f32_e32 v151, v253, v175
	s_waitcnt lgkmcnt(5)
	v_fmac_f32_e32 v136, v252, v176
	v_fmac_f32_e32 v152, v253, v176
	v_fmac_f32_e32 v137, v252, v177
	v_fmac_f32_e32 v153, v253, v177
	v_fmac_f32_e32 v138, v252, v178
	v_fmac_f32_e32 v154, v253, v178
	v_fmac_f32_e32 v139, v252, v179
	v_fmac_f32_e32 v155, v253, v179
	s_waitcnt lgkmcnt(4)
	v_fmac_f32_e32 v140, v252, v180
	v_fmac_f32_e32 v156, v253, v180
	v_fmac_f32_e32 v141, v252, v181
	v_fmac_f32_e32 v157, v253, v181
	v_fmac_f32_e32 v142, v252, v182
	v_fmac_f32_e32 v158, v253, v182
	v_fmac_f32_e32 v143, v252, v183
	v_fmac_f32_e32 v159, v253, v183
	ds_read_b128 v[168:171], v244 offset:40960
	ds_read_b128 v[172:175], v245 offset:40960
	ds_read_b128 v[176:179], v246 offset:40960
	ds_read_b128 v[180:183], v247 offset:40960
	v_mul_f32_e32 v252, v9, v209
	v_fmac_f32_e32 v254, v9, v9
	v_mul_f32_e32 v253, v41, v209
	v_fmac_f32_e32 v255, v41, v41
	s_waitcnt lgkmcnt(7)
	v_fmac_f32_e32 v128, v252, v184
	v_fmac_f32_e32 v144, v253, v184
	v_fmac_f32_e32 v129, v252, v185
	v_fmac_f32_e32 v145, v253, v185
	v_fmac_f32_e32 v130, v252, v186
	v_fmac_f32_e32 v146, v253, v186
	v_fmac_f32_e32 v131, v252, v187
	v_fmac_f32_e32 v147, v253, v187
	s_waitcnt lgkmcnt(6)
	v_fmac_f32_e32 v132, v252, v188
	v_fmac_f32_e32 v148, v253, v188
	v_fmac_f32_e32 v133, v252, v189
	v_fmac_f32_e32 v149, v253, v189
	v_fmac_f32_e32 v134, v252, v190
	v_fmac_f32_e32 v150, v253, v190
	v_fmac_f32_e32 v135, v252, v191
	v_fmac_f32_e32 v151, v253, v191
	s_waitcnt lgkmcnt(5)
	v_fmac_f32_e32 v136, v252, v232
	v_fmac_f32_e32 v152, v253, v232
	v_fmac_f32_e32 v137, v252, v233
	v_fmac_f32_e32 v153, v253, v233
	v_fmac_f32_e32 v138, v252, v234
	v_fmac_f32_e32 v154, v253, v234
	v_fmac_f32_e32 v139, v252, v235
	v_fmac_f32_e32 v155, v253, v235
	s_waitcnt lgkmcnt(4)
	v_fmac_f32_e32 v140, v252, v240
	v_fmac_f32_e32 v156, v253, v240
	v_fmac_f32_e32 v141, v252, v241
	v_fmac_f32_e32 v157, v253, v241
	v_fmac_f32_e32 v142, v252, v242
	v_fmac_f32_e32 v158, v253, v242
	v_fmac_f32_e32 v143, v252, v243
	v_fmac_f32_e32 v159, v253, v243
	ds_read_b128 v[184:187], v244 offset:45056
	ds_read_b128 v[188:191], v245 offset:45056
	ds_read_b128 v[232:235], v246 offset:45056
	ds_read_b128 v[240:243], v247 offset:45056
	v_mul_f32_e32 v252, v10, v210
	v_fmac_f32_e32 v254, v10, v10
	v_mul_f32_e32 v253, v42, v210
	v_fmac_f32_e32 v255, v42, v42
	s_waitcnt lgkmcnt(7)
	v_fmac_f32_e32 v128, v252, v168
	v_fmac_f32_e32 v144, v253, v168
	v_fmac_f32_e32 v129, v252, v169
	v_fmac_f32_e32 v145, v253, v169
	v_fmac_f32_e32 v130, v252, v170
	v_fmac_f32_e32 v146, v253, v170
	v_fmac_f32_e32 v131, v252, v171
	v_fmac_f32_e32 v147, v253, v171
	s_waitcnt lgkmcnt(6)
	v_fmac_f32_e32 v132, v252, v172
	v_fmac_f32_e32 v148, v253, v172
	v_fmac_f32_e32 v133, v252, v173
	v_fmac_f32_e32 v149, v253, v173
	v_fmac_f32_e32 v134, v252, v174
	v_fmac_f32_e32 v150, v253, v174
	v_fmac_f32_e32 v135, v252, v175
	v_fmac_f32_e32 v151, v253, v175
	s_waitcnt lgkmcnt(5)
	v_fmac_f32_e32 v136, v252, v176
	v_fmac_f32_e32 v152, v253, v176
	v_fmac_f32_e32 v137, v252, v177
	v_fmac_f32_e32 v153, v253, v177
	v_fmac_f32_e32 v138, v252, v178
	v_fmac_f32_e32 v154, v253, v178
	v_fmac_f32_e32 v139, v252, v179
	v_fmac_f32_e32 v155, v253, v179
	s_waitcnt lgkmcnt(4)
	v_fmac_f32_e32 v140, v252, v180
	v_fmac_f32_e32 v156, v253, v180
	v_fmac_f32_e32 v141, v252, v181
	v_fmac_f32_e32 v157, v253, v181
	v_fmac_f32_e32 v142, v252, v182
	v_fmac_f32_e32 v158, v253, v182
	v_fmac_f32_e32 v143, v252, v183
	v_fmac_f32_e32 v159, v253, v183
	ds_read_b128 v[168:171], v244 offset:49152
	ds_read_b128 v[172:175], v245 offset:49152
	ds_read_b128 v[176:179], v246 offset:49152
	ds_read_b128 v[180:183], v247 offset:49152
	v_mul_f32_e32 v252, v11, v211
	v_fmac_f32_e32 v254, v11, v11
	v_mul_f32_e32 v253, v43, v211
	v_fmac_f32_e32 v255, v43, v43
	s_waitcnt lgkmcnt(7)
	v_fmac_f32_e32 v128, v252, v184
	v_fmac_f32_e32 v144, v253, v184
	v_fmac_f32_e32 v129, v252, v185
	v_fmac_f32_e32 v145, v253, v185
	v_fmac_f32_e32 v130, v252, v186
	v_fmac_f32_e32 v146, v253, v186
	v_fmac_f32_e32 v131, v252, v187
	v_fmac_f32_e32 v147, v253, v187
	s_waitcnt lgkmcnt(6)
	v_fmac_f32_e32 v132, v252, v188
	v_fmac_f32_e32 v148, v253, v188
	v_fmac_f32_e32 v133, v252, v189
	v_fmac_f32_e32 v149, v253, v189
	v_fmac_f32_e32 v134, v252, v190
	v_fmac_f32_e32 v150, v253, v190
	v_fmac_f32_e32 v135, v252, v191
	v_fmac_f32_e32 v151, v253, v191
	s_waitcnt lgkmcnt(5)
	v_fmac_f32_e32 v136, v252, v232
	v_fmac_f32_e32 v152, v253, v232
	v_fmac_f32_e32 v137, v252, v233
	v_fmac_f32_e32 v153, v253, v233
	v_fmac_f32_e32 v138, v252, v234
	v_fmac_f32_e32 v154, v253, v234
	v_fmac_f32_e32 v139, v252, v235
	v_fmac_f32_e32 v155, v253, v235
	s_waitcnt lgkmcnt(4)
	v_fmac_f32_e32 v140, v252, v240
	v_fmac_f32_e32 v156, v253, v240
	v_fmac_f32_e32 v141, v252, v241
	v_fmac_f32_e32 v157, v253, v241
	v_fmac_f32_e32 v142, v252, v242
	v_fmac_f32_e32 v158, v253, v242
	v_fmac_f32_e32 v143, v252, v243
	v_fmac_f32_e32 v159, v253, v243
	ds_read_b128 v[184:187], v244 offset:53248
	ds_read_b128 v[188:191], v245 offset:53248
	ds_read_b128 v[232:235], v246 offset:53248
	ds_read_b128 v[240:243], v247 offset:53248
	v_mul_f32_e32 v252, v12, v212
	v_fmac_f32_e32 v254, v12, v12
	v_mul_f32_e32 v253, v44, v212
	v_fmac_f32_e32 v255, v44, v44
	s_waitcnt lgkmcnt(7)
	v_fmac_f32_e32 v128, v252, v168
	v_fmac_f32_e32 v144, v253, v168
	v_fmac_f32_e32 v129, v252, v169
	v_fmac_f32_e32 v145, v253, v169
	v_fmac_f32_e32 v130, v252, v170
	v_fmac_f32_e32 v146, v253, v170
	v_fmac_f32_e32 v131, v252, v171
	v_fmac_f32_e32 v147, v253, v171
	s_waitcnt lgkmcnt(6)
	v_fmac_f32_e32 v132, v252, v172
	v_fmac_f32_e32 v148, v253, v172
	v_fmac_f32_e32 v133, v252, v173
	v_fmac_f32_e32 v149, v253, v173
	v_fmac_f32_e32 v134, v252, v174
	v_fmac_f32_e32 v150, v253, v174
	v_fmac_f32_e32 v135, v252, v175
	v_fmac_f32_e32 v151, v253, v175
	s_waitcnt lgkmcnt(5)
	v_fmac_f32_e32 v136, v252, v176
	v_fmac_f32_e32 v152, v253, v176
	v_fmac_f32_e32 v137, v252, v177
	v_fmac_f32_e32 v153, v253, v177
	v_fmac_f32_e32 v138, v252, v178
	v_fmac_f32_e32 v154, v253, v178
	v_fmac_f32_e32 v139, v252, v179
	v_fmac_f32_e32 v155, v253, v179
	s_waitcnt lgkmcnt(4)
	v_fmac_f32_e32 v140, v252, v180
	v_fmac_f32_e32 v156, v253, v180
	v_fmac_f32_e32 v141, v252, v181
	v_fmac_f32_e32 v157, v253, v181
	v_fmac_f32_e32 v142, v252, v182
	v_fmac_f32_e32 v158, v253, v182
	v_fmac_f32_e32 v143, v252, v183
	v_fmac_f32_e32 v159, v253, v183
	ds_read_b128 v[168:171], v244 offset:57344
	ds_read_b128 v[172:175], v245 offset:57344
	ds_read_b128 v[176:179], v246 offset:57344
	ds_read_b128 v[180:183], v247 offset:57344
	v_mul_f32_e32 v252, v13, v213
	v_fmac_f32_e32 v254, v13, v13
	v_mul_f32_e32 v253, v45, v213
	v_fmac_f32_e32 v255, v45, v45
	s_waitcnt lgkmcnt(7)
	v_fmac_f32_e32 v128, v252, v184
	v_fmac_f32_e32 v144, v253, v184
	v_fmac_f32_e32 v129, v252, v185
	v_fmac_f32_e32 v145, v253, v185
	v_fmac_f32_e32 v130, v252, v186
	v_fmac_f32_e32 v146, v253, v186
	v_fmac_f32_e32 v131, v252, v187
	v_fmac_f32_e32 v147, v253, v187
	s_waitcnt lgkmcnt(6)
	v_fmac_f32_e32 v132, v252, v188
	v_fmac_f32_e32 v148, v253, v188
	v_fmac_f32_e32 v133, v252, v189
	v_fmac_f32_e32 v149, v253, v189
	v_fmac_f32_e32 v134, v252, v190
	v_fmac_f32_e32 v150, v253, v190
	v_fmac_f32_e32 v135, v252, v191
	v_fmac_f32_e32 v151, v253, v191
	s_waitcnt lgkmcnt(5)
	v_fmac_f32_e32 v136, v252, v232
	v_fmac_f32_e32 v152, v253, v232
	v_fmac_f32_e32 v137, v252, v233
	v_fmac_f32_e32 v153, v253, v233
	v_fmac_f32_e32 v138, v252, v234
	v_fmac_f32_e32 v154, v253, v234
	v_fmac_f32_e32 v139, v252, v235
	v_fmac_f32_e32 v155, v253, v235
	s_waitcnt lgkmcnt(4)
	v_fmac_f32_e32 v140, v252, v240
	v_fmac_f32_e32 v156, v253, v240
	v_fmac_f32_e32 v141, v252, v241
	v_fmac_f32_e32 v157, v253, v241
	v_fmac_f32_e32 v142, v252, v242
	v_fmac_f32_e32 v158, v253, v242
	v_fmac_f32_e32 v143, v252, v243
	v_fmac_f32_e32 v159, v253, v243
	ds_read_b128 v[184:187], v244 offset:61440
	ds_read_b128 v[188:191], v245 offset:61440
	ds_read_b128 v[232:235], v246 offset:61440
	ds_read_b128 v[240:243], v247 offset:61440
	v_mul_f32_e32 v252, v14, v214
	v_fmac_f32_e32 v254, v14, v14
	v_mul_f32_e32 v253, v46, v214
	v_fmac_f32_e32 v255, v46, v46
	s_waitcnt lgkmcnt(7)
	v_fmac_f32_e32 v128, v252, v168
	v_fmac_f32_e32 v144, v253, v168
	v_fmac_f32_e32 v129, v252, v169
	v_fmac_f32_e32 v145, v253, v169
	v_fmac_f32_e32 v130, v252, v170
	v_fmac_f32_e32 v146, v253, v170
	v_fmac_f32_e32 v131, v252, v171
	v_fmac_f32_e32 v147, v253, v171
	s_waitcnt lgkmcnt(6)
	v_fmac_f32_e32 v132, v252, v172
	v_fmac_f32_e32 v148, v253, v172
	v_fmac_f32_e32 v133, v252, v173
	v_fmac_f32_e32 v149, v253, v173
	v_fmac_f32_e32 v134, v252, v174
	v_fmac_f32_e32 v150, v253, v174
	v_fmac_f32_e32 v135, v252, v175
	v_fmac_f32_e32 v151, v253, v175
	s_waitcnt lgkmcnt(5)
	v_fmac_f32_e32 v136, v252, v176
	v_fmac_f32_e32 v152, v253, v176
	v_fmac_f32_e32 v137, v252, v177
	v_fmac_f32_e32 v153, v253, v177
	v_fmac_f32_e32 v138, v252, v178
	v_fmac_f32_e32 v154, v253, v178
	v_fmac_f32_e32 v139, v252, v179
	v_fmac_f32_e32 v155, v253, v179
	s_waitcnt lgkmcnt(4)
	v_fmac_f32_e32 v140, v252, v180
	v_fmac_f32_e32 v156, v253, v180
	v_fmac_f32_e32 v141, v252, v181
	v_fmac_f32_e32 v157, v253, v181
	v_fmac_f32_e32 v142, v252, v182
	v_fmac_f32_e32 v158, v253, v182
	v_fmac_f32_e32 v143, v252, v183
	v_fmac_f32_e32 v159, v253, v183
	ds_read_b128 v[168:171], v248 offset:0
	ds_read_b128 v[172:175], v249 offset:0
	ds_read_b128 v[176:179], v250 offset:0
	ds_read_b128 v[180:183], v251 offset:0
	v_mul_f32_e32 v252, v15, v215
	v_fmac_f32_e32 v254, v15, v15
	v_mul_f32_e32 v253, v47, v215
	v_fmac_f32_e32 v255, v47, v47
	s_waitcnt lgkmcnt(7)
	v_fmac_f32_e32 v128, v252, v184
	v_fmac_f32_e32 v144, v253, v184
	v_fmac_f32_e32 v129, v252, v185
	v_fmac_f32_e32 v145, v253, v185
	v_fmac_f32_e32 v130, v252, v186
	v_fmac_f32_e32 v146, v253, v186
	v_fmac_f32_e32 v131, v252, v187
	v_fmac_f32_e32 v147, v253, v187
	s_waitcnt lgkmcnt(6)
	v_fmac_f32_e32 v132, v252, v188
	v_fmac_f32_e32 v148, v253, v188
	v_fmac_f32_e32 v133, v252, v189
	v_fmac_f32_e32 v149, v253, v189
	v_fmac_f32_e32 v134, v252, v190
	v_fmac_f32_e32 v150, v253, v190
	v_fmac_f32_e32 v135, v252, v191
	v_fmac_f32_e32 v151, v253, v191
	s_waitcnt lgkmcnt(5)
	v_fmac_f32_e32 v136, v252, v232
	v_fmac_f32_e32 v152, v253, v232
	v_fmac_f32_e32 v137, v252, v233
	v_fmac_f32_e32 v153, v253, v233
	v_fmac_f32_e32 v138, v252, v234
	v_fmac_f32_e32 v154, v253, v234
	v_fmac_f32_e32 v139, v252, v235
	v_fmac_f32_e32 v155, v253, v235
	s_waitcnt lgkmcnt(4)
	v_fmac_f32_e32 v140, v252, v240
	v_fmac_f32_e32 v156, v253, v240
	v_fmac_f32_e32 v141, v252, v241
	v_fmac_f32_e32 v157, v253, v241
	v_fmac_f32_e32 v142, v252, v242
	v_fmac_f32_e32 v158, v253, v242
	v_fmac_f32_e32 v143, v252, v243
	v_fmac_f32_e32 v159, v253, v243
	ds_read_b128 v[184:187], v248 offset:4096
	ds_read_b128 v[188:191], v249 offset:4096
	ds_read_b128 v[232:235], v250 offset:4096
	ds_read_b128 v[240:243], v251 offset:4096
	v_mul_f32_e32 v252, v16, v216
	v_fmac_f32_e32 v254, v16, v16
	v_mul_f32_e32 v253, v48, v216
	v_fmac_f32_e32 v255, v48, v48
	s_waitcnt lgkmcnt(7)
	v_fmac_f32_e32 v128, v252, v168
	v_fmac_f32_e32 v144, v253, v168
	v_fmac_f32_e32 v129, v252, v169
	v_fmac_f32_e32 v145, v253, v169
	v_fmac_f32_e32 v130, v252, v170
	v_fmac_f32_e32 v146, v253, v170
	v_fmac_f32_e32 v131, v252, v171
	v_fmac_f32_e32 v147, v253, v171
	s_waitcnt lgkmcnt(6)
	v_fmac_f32_e32 v132, v252, v172
	v_fmac_f32_e32 v148, v253, v172
	v_fmac_f32_e32 v133, v252, v173
	v_fmac_f32_e32 v149, v253, v173
	v_fmac_f32_e32 v134, v252, v174
	v_fmac_f32_e32 v150, v253, v174
	v_fmac_f32_e32 v135, v252, v175
	v_fmac_f32_e32 v151, v253, v175
	s_waitcnt lgkmcnt(5)
	v_fmac_f32_e32 v136, v252, v176
	v_fmac_f32_e32 v152, v253, v176
	v_fmac_f32_e32 v137, v252, v177
	v_fmac_f32_e32 v153, v253, v177
	v_fmac_f32_e32 v138, v252, v178
	v_fmac_f32_e32 v154, v253, v178
	v_fmac_f32_e32 v139, v252, v179
	v_fmac_f32_e32 v155, v253, v179
	s_waitcnt lgkmcnt(4)
	v_fmac_f32_e32 v140, v252, v180
	v_fmac_f32_e32 v156, v253, v180
	v_fmac_f32_e32 v141, v252, v181
	v_fmac_f32_e32 v157, v253, v181
	v_fmac_f32_e32 v142, v252, v182
	v_fmac_f32_e32 v158, v253, v182
	v_fmac_f32_e32 v143, v252, v183
	v_fmac_f32_e32 v159, v253, v183
	ds_read_b128 v[168:171], v248 offset:8192
	ds_read_b128 v[172:175], v249 offset:8192
	ds_read_b128 v[176:179], v250 offset:8192
	ds_read_b128 v[180:183], v251 offset:8192
	v_mul_f32_e32 v252, v17, v217
	v_fmac_f32_e32 v254, v17, v17
	v_mul_f32_e32 v253, v49, v217
	v_fmac_f32_e32 v255, v49, v49
	s_waitcnt lgkmcnt(7)
	v_fmac_f32_e32 v128, v252, v184
	v_fmac_f32_e32 v144, v253, v184
	v_fmac_f32_e32 v129, v252, v185
	v_fmac_f32_e32 v145, v253, v185
	v_fmac_f32_e32 v130, v252, v186
	v_fmac_f32_e32 v146, v253, v186
	v_fmac_f32_e32 v131, v252, v187
	v_fmac_f32_e32 v147, v253, v187
	s_waitcnt lgkmcnt(6)
	v_fmac_f32_e32 v132, v252, v188
	v_fmac_f32_e32 v148, v253, v188
	v_fmac_f32_e32 v133, v252, v189
	v_fmac_f32_e32 v149, v253, v189
	v_fmac_f32_e32 v134, v252, v190
	v_fmac_f32_e32 v150, v253, v190
	v_fmac_f32_e32 v135, v252, v191
	v_fmac_f32_e32 v151, v253, v191
	s_waitcnt lgkmcnt(5)
	v_fmac_f32_e32 v136, v252, v232
	v_fmac_f32_e32 v152, v253, v232
	v_fmac_f32_e32 v137, v252, v233
	v_fmac_f32_e32 v153, v253, v233
	v_fmac_f32_e32 v138, v252, v234
	v_fmac_f32_e32 v154, v253, v234
	v_fmac_f32_e32 v139, v252, v235
	v_fmac_f32_e32 v155, v253, v235
	s_waitcnt lgkmcnt(4)
	v_fmac_f32_e32 v140, v252, v240
	v_fmac_f32_e32 v156, v253, v240
	v_fmac_f32_e32 v141, v252, v241
	v_fmac_f32_e32 v157, v253, v241
	v_fmac_f32_e32 v142, v252, v242
	v_fmac_f32_e32 v158, v253, v242
	v_fmac_f32_e32 v143, v252, v243
	v_fmac_f32_e32 v159, v253, v243
	ds_read_b128 v[184:187], v248 offset:12288
	ds_read_b128 v[188:191], v249 offset:12288
	ds_read_b128 v[232:235], v250 offset:12288
	ds_read_b128 v[240:243], v251 offset:12288
	v_mul_f32_e32 v252, v18, v218
	v_fmac_f32_e32 v254, v18, v18
	v_mul_f32_e32 v253, v50, v218
	v_fmac_f32_e32 v255, v50, v50
	s_waitcnt lgkmcnt(7)
	v_fmac_f32_e32 v128, v252, v168
	v_fmac_f32_e32 v144, v253, v168
	v_fmac_f32_e32 v129, v252, v169
	v_fmac_f32_e32 v145, v253, v169
	v_fmac_f32_e32 v130, v252, v170
	v_fmac_f32_e32 v146, v253, v170
	v_fmac_f32_e32 v131, v252, v171
	v_fmac_f32_e32 v147, v253, v171
	s_waitcnt lgkmcnt(6)
	v_fmac_f32_e32 v132, v252, v172
	v_fmac_f32_e32 v148, v253, v172
	v_fmac_f32_e32 v133, v252, v173
	v_fmac_f32_e32 v149, v253, v173
	v_fmac_f32_e32 v134, v252, v174
	v_fmac_f32_e32 v150, v253, v174
	v_fmac_f32_e32 v135, v252, v175
	v_fmac_f32_e32 v151, v253, v175
	s_waitcnt lgkmcnt(5)
	v_fmac_f32_e32 v136, v252, v176
	v_fmac_f32_e32 v152, v253, v176
	v_fmac_f32_e32 v137, v252, v177
	v_fmac_f32_e32 v153, v253, v177
	v_fmac_f32_e32 v138, v252, v178
	v_fmac_f32_e32 v154, v253, v178
	v_fmac_f32_e32 v139, v252, v179
	v_fmac_f32_e32 v155, v253, v179
	s_waitcnt lgkmcnt(4)
	v_fmac_f32_e32 v140, v252, v180
	v_fmac_f32_e32 v156, v253, v180
	v_fmac_f32_e32 v141, v252, v181
	v_fmac_f32_e32 v157, v253, v181
	v_fmac_f32_e32 v142, v252, v182
	v_fmac_f32_e32 v158, v253, v182
	v_fmac_f32_e32 v143, v252, v183
	v_fmac_f32_e32 v159, v253, v183
	ds_read_b128 v[168:171], v248 offset:16384
	ds_read_b128 v[172:175], v249 offset:16384
	ds_read_b128 v[176:179], v250 offset:16384
	ds_read_b128 v[180:183], v251 offset:16384
	v_mul_f32_e32 v252, v19, v219
	v_fmac_f32_e32 v254, v19, v19
	v_mul_f32_e32 v253, v51, v219
	v_fmac_f32_e32 v255, v51, v51
	s_waitcnt lgkmcnt(7)
	v_fmac_f32_e32 v128, v252, v184
	v_fmac_f32_e32 v144, v253, v184
	v_fmac_f32_e32 v129, v252, v185
	v_fmac_f32_e32 v145, v253, v185
	v_fmac_f32_e32 v130, v252, v186
	v_fmac_f32_e32 v146, v253, v186
	v_fmac_f32_e32 v131, v252, v187
	v_fmac_f32_e32 v147, v253, v187
	s_waitcnt lgkmcnt(6)
	v_fmac_f32_e32 v132, v252, v188
	v_fmac_f32_e32 v148, v253, v188
	v_fmac_f32_e32 v133, v252, v189
	v_fmac_f32_e32 v149, v253, v189
	v_fmac_f32_e32 v134, v252, v190
	v_fmac_f32_e32 v150, v253, v190
	v_fmac_f32_e32 v135, v252, v191
	v_fmac_f32_e32 v151, v253, v191
	s_waitcnt lgkmcnt(5)
	v_fmac_f32_e32 v136, v252, v232
	v_fmac_f32_e32 v152, v253, v232
	v_fmac_f32_e32 v137, v252, v233
	v_fmac_f32_e32 v153, v253, v233
	v_fmac_f32_e32 v138, v252, v234
	v_fmac_f32_e32 v154, v253, v234
	v_fmac_f32_e32 v139, v252, v235
	v_fmac_f32_e32 v155, v253, v235
	s_waitcnt lgkmcnt(4)
	v_fmac_f32_e32 v140, v252, v240
	v_fmac_f32_e32 v156, v253, v240
	v_fmac_f32_e32 v141, v252, v241
	v_fmac_f32_e32 v157, v253, v241
	v_fmac_f32_e32 v142, v252, v242
	v_fmac_f32_e32 v158, v253, v242
	v_fmac_f32_e32 v143, v252, v243
	v_fmac_f32_e32 v159, v253, v243
	ds_read_b128 v[184:187], v248 offset:20480
	ds_read_b128 v[188:191], v249 offset:20480
	ds_read_b128 v[232:235], v250 offset:20480
	ds_read_b128 v[240:243], v251 offset:20480
	v_mul_f32_e32 v252, v20, v220
	v_fmac_f32_e32 v254, v20, v20
	v_mul_f32_e32 v253, v52, v220
	v_fmac_f32_e32 v255, v52, v52
	s_waitcnt lgkmcnt(7)
	v_fmac_f32_e32 v128, v252, v168
	v_fmac_f32_e32 v144, v253, v168
	v_fmac_f32_e32 v129, v252, v169
	v_fmac_f32_e32 v145, v253, v169
	v_fmac_f32_e32 v130, v252, v170
	v_fmac_f32_e32 v146, v253, v170
	v_fmac_f32_e32 v131, v252, v171
	v_fmac_f32_e32 v147, v253, v171
	s_waitcnt lgkmcnt(6)
	v_fmac_f32_e32 v132, v252, v172
	v_fmac_f32_e32 v148, v253, v172
	v_fmac_f32_e32 v133, v252, v173
	v_fmac_f32_e32 v149, v253, v173
	v_fmac_f32_e32 v134, v252, v174
	v_fmac_f32_e32 v150, v253, v174
	v_fmac_f32_e32 v135, v252, v175
	v_fmac_f32_e32 v151, v253, v175
	s_waitcnt lgkmcnt(5)
	v_fmac_f32_e32 v136, v252, v176
	v_fmac_f32_e32 v152, v253, v176
	v_fmac_f32_e32 v137, v252, v177
	v_fmac_f32_e32 v153, v253, v177
	v_fmac_f32_e32 v138, v252, v178
	v_fmac_f32_e32 v154, v253, v178
	v_fmac_f32_e32 v139, v252, v179
	v_fmac_f32_e32 v155, v253, v179
	s_waitcnt lgkmcnt(4)
	v_fmac_f32_e32 v140, v252, v180
	v_fmac_f32_e32 v156, v253, v180
	v_fmac_f32_e32 v141, v252, v181
	v_fmac_f32_e32 v157, v253, v181
	v_fmac_f32_e32 v142, v252, v182
	v_fmac_f32_e32 v158, v253, v182
	v_fmac_f32_e32 v143, v252, v183
	v_fmac_f32_e32 v159, v253, v183
	ds_read_b128 v[168:171], v248 offset:24576
	ds_read_b128 v[172:175], v249 offset:24576
	ds_read_b128 v[176:179], v250 offset:24576
	ds_read_b128 v[180:183], v251 offset:24576
	v_mul_f32_e32 v252, v21, v221
	v_fmac_f32_e32 v254, v21, v21
	v_mul_f32_e32 v253, v53, v221
	v_fmac_f32_e32 v255, v53, v53
	s_waitcnt lgkmcnt(7)
	v_fmac_f32_e32 v128, v252, v184
	v_fmac_f32_e32 v144, v253, v184
	v_fmac_f32_e32 v129, v252, v185
	v_fmac_f32_e32 v145, v253, v185
	v_fmac_f32_e32 v130, v252, v186
	v_fmac_f32_e32 v146, v253, v186
	v_fmac_f32_e32 v131, v252, v187
	v_fmac_f32_e32 v147, v253, v187
	s_waitcnt lgkmcnt(6)
	v_fmac_f32_e32 v132, v252, v188
	v_fmac_f32_e32 v148, v253, v188
	v_fmac_f32_e32 v133, v252, v189
	v_fmac_f32_e32 v149, v253, v189
	v_fmac_f32_e32 v134, v252, v190
	v_fmac_f32_e32 v150, v253, v190
	v_fmac_f32_e32 v135, v252, v191
	v_fmac_f32_e32 v151, v253, v191
	s_waitcnt lgkmcnt(5)
	v_fmac_f32_e32 v136, v252, v232
	v_fmac_f32_e32 v152, v253, v232
	v_fmac_f32_e32 v137, v252, v233
	v_fmac_f32_e32 v153, v253, v233
	v_fmac_f32_e32 v138, v252, v234
	v_fmac_f32_e32 v154, v253, v234
	v_fmac_f32_e32 v139, v252, v235
	v_fmac_f32_e32 v155, v253, v235
	s_waitcnt lgkmcnt(4)
	v_fmac_f32_e32 v140, v252, v240
	v_fmac_f32_e32 v156, v253, v240
	v_fmac_f32_e32 v141, v252, v241
	v_fmac_f32_e32 v157, v253, v241
	v_fmac_f32_e32 v142, v252, v242
	v_fmac_f32_e32 v158, v253, v242
	v_fmac_f32_e32 v143, v252, v243
	v_fmac_f32_e32 v159, v253, v243
	ds_read_b128 v[184:187], v248 offset:28672
	ds_read_b128 v[188:191], v249 offset:28672
	ds_read_b128 v[232:235], v250 offset:28672
	ds_read_b128 v[240:243], v251 offset:28672
	v_mul_f32_e32 v252, v22, v222
	v_fmac_f32_e32 v254, v22, v22
	v_mul_f32_e32 v253, v54, v222
	v_fmac_f32_e32 v255, v54, v54
	s_waitcnt lgkmcnt(7)
	v_fmac_f32_e32 v128, v252, v168
	v_fmac_f32_e32 v144, v253, v168
	v_fmac_f32_e32 v129, v252, v169
	v_fmac_f32_e32 v145, v253, v169
	v_fmac_f32_e32 v130, v252, v170
	v_fmac_f32_e32 v146, v253, v170
	v_fmac_f32_e32 v131, v252, v171
	v_fmac_f32_e32 v147, v253, v171
	s_waitcnt lgkmcnt(6)
	v_fmac_f32_e32 v132, v252, v172
	v_fmac_f32_e32 v148, v253, v172
	v_fmac_f32_e32 v133, v252, v173
	v_fmac_f32_e32 v149, v253, v173
	v_fmac_f32_e32 v134, v252, v174
	v_fmac_f32_e32 v150, v253, v174
	v_fmac_f32_e32 v135, v252, v175
	v_fmac_f32_e32 v151, v253, v175
	s_waitcnt lgkmcnt(5)
	v_fmac_f32_e32 v136, v252, v176
	v_fmac_f32_e32 v152, v253, v176
	v_fmac_f32_e32 v137, v252, v177
	v_fmac_f32_e32 v153, v253, v177
	v_fmac_f32_e32 v138, v252, v178
	v_fmac_f32_e32 v154, v253, v178
	v_fmac_f32_e32 v139, v252, v179
	v_fmac_f32_e32 v155, v253, v179
	s_waitcnt lgkmcnt(4)
	v_fmac_f32_e32 v140, v252, v180
	v_fmac_f32_e32 v156, v253, v180
	v_fmac_f32_e32 v141, v252, v181
	v_fmac_f32_e32 v157, v253, v181
	v_fmac_f32_e32 v142, v252, v182
	v_fmac_f32_e32 v158, v253, v182
	v_fmac_f32_e32 v143, v252, v183
	v_fmac_f32_e32 v159, v253, v183
	ds_read_b128 v[168:171], v248 offset:32768
	ds_read_b128 v[172:175], v249 offset:32768
	ds_read_b128 v[176:179], v250 offset:32768
	ds_read_b128 v[180:183], v251 offset:32768
	v_mul_f32_e32 v252, v23, v223
	v_fmac_f32_e32 v254, v23, v23
	v_mul_f32_e32 v253, v55, v223
	v_fmac_f32_e32 v255, v55, v55
	s_waitcnt lgkmcnt(7)
	v_fmac_f32_e32 v128, v252, v184
	v_fmac_f32_e32 v144, v253, v184
	v_fmac_f32_e32 v129, v252, v185
	v_fmac_f32_e32 v145, v253, v185
	v_fmac_f32_e32 v130, v252, v186
	v_fmac_f32_e32 v146, v253, v186
	v_fmac_f32_e32 v131, v252, v187
	v_fmac_f32_e32 v147, v253, v187
	s_waitcnt lgkmcnt(6)
	v_fmac_f32_e32 v132, v252, v188
	v_fmac_f32_e32 v148, v253, v188
	v_fmac_f32_e32 v133, v252, v189
	v_fmac_f32_e32 v149, v253, v189
	v_fmac_f32_e32 v134, v252, v190
	v_fmac_f32_e32 v150, v253, v190
	v_fmac_f32_e32 v135, v252, v191
	v_fmac_f32_e32 v151, v253, v191
	s_waitcnt lgkmcnt(5)
	v_fmac_f32_e32 v136, v252, v232
	v_fmac_f32_e32 v152, v253, v232
	v_fmac_f32_e32 v137, v252, v233
	v_fmac_f32_e32 v153, v253, v233
	v_fmac_f32_e32 v138, v252, v234
	v_fmac_f32_e32 v154, v253, v234
	v_fmac_f32_e32 v139, v252, v235
	v_fmac_f32_e32 v155, v253, v235
	s_waitcnt lgkmcnt(4)
	v_fmac_f32_e32 v140, v252, v240
	v_fmac_f32_e32 v156, v253, v240
	v_fmac_f32_e32 v141, v252, v241
	v_fmac_f32_e32 v157, v253, v241
	v_fmac_f32_e32 v142, v252, v242
	v_fmac_f32_e32 v158, v253, v242
	v_fmac_f32_e32 v143, v252, v243
	v_fmac_f32_e32 v159, v253, v243
	ds_read_b128 v[184:187], v248 offset:36864
	ds_read_b128 v[188:191], v249 offset:36864
	ds_read_b128 v[232:235], v250 offset:36864
	ds_read_b128 v[240:243], v251 offset:36864
	v_mul_f32_e32 v252, v24, v224
	v_fmac_f32_e32 v254, v24, v24
	v_mul_f32_e32 v253, v56, v224
	v_fmac_f32_e32 v255, v56, v56
	s_waitcnt lgkmcnt(7)
	v_fmac_f32_e32 v128, v252, v168
	v_fmac_f32_e32 v144, v253, v168
	v_fmac_f32_e32 v129, v252, v169
	v_fmac_f32_e32 v145, v253, v169
	v_fmac_f32_e32 v130, v252, v170
	v_fmac_f32_e32 v146, v253, v170
	v_fmac_f32_e32 v131, v252, v171
	v_fmac_f32_e32 v147, v253, v171
	s_waitcnt lgkmcnt(6)
	v_fmac_f32_e32 v132, v252, v172
	v_fmac_f32_e32 v148, v253, v172
	v_fmac_f32_e32 v133, v252, v173
	v_fmac_f32_e32 v149, v253, v173
	v_fmac_f32_e32 v134, v252, v174
	v_fmac_f32_e32 v150, v253, v174
	v_fmac_f32_e32 v135, v252, v175
	v_fmac_f32_e32 v151, v253, v175
	s_waitcnt lgkmcnt(5)
	v_fmac_f32_e32 v136, v252, v176
	v_fmac_f32_e32 v152, v253, v176
	v_fmac_f32_e32 v137, v252, v177
	v_fmac_f32_e32 v153, v253, v177
	v_fmac_f32_e32 v138, v252, v178
	v_fmac_f32_e32 v154, v253, v178
	v_fmac_f32_e32 v139, v252, v179
	v_fmac_f32_e32 v155, v253, v179
	s_waitcnt lgkmcnt(4)
	v_fmac_f32_e32 v140, v252, v180
	v_fmac_f32_e32 v156, v253, v180
	v_fmac_f32_e32 v141, v252, v181
	v_fmac_f32_e32 v157, v253, v181
	v_fmac_f32_e32 v142, v252, v182
	v_fmac_f32_e32 v158, v253, v182
	v_fmac_f32_e32 v143, v252, v183
	v_fmac_f32_e32 v159, v253, v183
	ds_read_b128 v[168:171], v248 offset:40960
	ds_read_b128 v[172:175], v249 offset:40960
	ds_read_b128 v[176:179], v250 offset:40960
	ds_read_b128 v[180:183], v251 offset:40960
	v_mul_f32_e32 v252, v25, v225
	v_fmac_f32_e32 v254, v25, v25
	v_mul_f32_e32 v253, v57, v225
	v_fmac_f32_e32 v255, v57, v57
	s_waitcnt lgkmcnt(7)
	v_fmac_f32_e32 v128, v252, v184
	v_fmac_f32_e32 v144, v253, v184
	v_fmac_f32_e32 v129, v252, v185
	v_fmac_f32_e32 v145, v253, v185
	v_fmac_f32_e32 v130, v252, v186
	v_fmac_f32_e32 v146, v253, v186
	v_fmac_f32_e32 v131, v252, v187
	v_fmac_f32_e32 v147, v253, v187
	s_waitcnt lgkmcnt(6)
	v_fmac_f32_e32 v132, v252, v188
	v_fmac_f32_e32 v148, v253, v188
	v_fmac_f32_e32 v133, v252, v189
	v_fmac_f32_e32 v149, v253, v189
	v_fmac_f32_e32 v134, v252, v190
	v_fmac_f32_e32 v150, v253, v190
	v_fmac_f32_e32 v135, v252, v191
	v_fmac_f32_e32 v151, v253, v191
	s_waitcnt lgkmcnt(5)
	v_fmac_f32_e32 v136, v252, v232
	v_fmac_f32_e32 v152, v253, v232
	v_fmac_f32_e32 v137, v252, v233
	v_fmac_f32_e32 v153, v253, v233
	v_fmac_f32_e32 v138, v252, v234
	v_fmac_f32_e32 v154, v253, v234
	v_fmac_f32_e32 v139, v252, v235
	v_fmac_f32_e32 v155, v253, v235
	s_waitcnt lgkmcnt(4)
	v_fmac_f32_e32 v140, v252, v240
	v_fmac_f32_e32 v156, v253, v240
	v_fmac_f32_e32 v141, v252, v241
	v_fmac_f32_e32 v157, v253, v241
	v_fmac_f32_e32 v142, v252, v242
	v_fmac_f32_e32 v158, v253, v242
	v_fmac_f32_e32 v143, v252, v243
	v_fmac_f32_e32 v159, v253, v243
	ds_read_b128 v[184:187], v248 offset:45056
	ds_read_b128 v[188:191], v249 offset:45056
	ds_read_b128 v[232:235], v250 offset:45056
	ds_read_b128 v[240:243], v251 offset:45056
	v_mul_f32_e32 v252, v26, v226
	v_fmac_f32_e32 v254, v26, v26
	v_mul_f32_e32 v253, v58, v226
	v_fmac_f32_e32 v255, v58, v58
	s_waitcnt lgkmcnt(7)
	v_fmac_f32_e32 v128, v252, v168
	v_fmac_f32_e32 v144, v253, v168
	v_fmac_f32_e32 v129, v252, v169
	v_fmac_f32_e32 v145, v253, v169
	v_fmac_f32_e32 v130, v252, v170
	v_fmac_f32_e32 v146, v253, v170
	v_fmac_f32_e32 v131, v252, v171
	v_fmac_f32_e32 v147, v253, v171
	s_waitcnt lgkmcnt(6)
	v_fmac_f32_e32 v132, v252, v172
	v_fmac_f32_e32 v148, v253, v172
	v_fmac_f32_e32 v133, v252, v173
	v_fmac_f32_e32 v149, v253, v173
	v_fmac_f32_e32 v134, v252, v174
	v_fmac_f32_e32 v150, v253, v174
	v_fmac_f32_e32 v135, v252, v175
	v_fmac_f32_e32 v151, v253, v175
	s_waitcnt lgkmcnt(5)
	v_fmac_f32_e32 v136, v252, v176
	v_fmac_f32_e32 v152, v253, v176
	v_fmac_f32_e32 v137, v252, v177
	v_fmac_f32_e32 v153, v253, v177
	v_fmac_f32_e32 v138, v252, v178
	v_fmac_f32_e32 v154, v253, v178
	v_fmac_f32_e32 v139, v252, v179
	v_fmac_f32_e32 v155, v253, v179
	s_waitcnt lgkmcnt(4)
	v_fmac_f32_e32 v140, v252, v180
	v_fmac_f32_e32 v156, v253, v180
	v_fmac_f32_e32 v141, v252, v181
	v_fmac_f32_e32 v157, v253, v181
	v_fmac_f32_e32 v142, v252, v182
	v_fmac_f32_e32 v158, v253, v182
	v_fmac_f32_e32 v143, v252, v183
	v_fmac_f32_e32 v159, v253, v183
	ds_read_b128 v[168:171], v248 offset:49152
	ds_read_b128 v[172:175], v249 offset:49152
	ds_read_b128 v[176:179], v250 offset:49152
	ds_read_b128 v[180:183], v251 offset:49152
	v_mul_f32_e32 v252, v27, v227
	v_fmac_f32_e32 v254, v27, v27
	v_mul_f32_e32 v253, v59, v227
	v_fmac_f32_e32 v255, v59, v59
	s_waitcnt lgkmcnt(7)
	v_fmac_f32_e32 v128, v252, v184
	v_fmac_f32_e32 v144, v253, v184
	v_fmac_f32_e32 v129, v252, v185
	v_fmac_f32_e32 v145, v253, v185
	v_fmac_f32_e32 v130, v252, v186
	v_fmac_f32_e32 v146, v253, v186
	v_fmac_f32_e32 v131, v252, v187
	v_fmac_f32_e32 v147, v253, v187
	s_waitcnt lgkmcnt(6)
	v_fmac_f32_e32 v132, v252, v188
	v_fmac_f32_e32 v148, v253, v188
	v_fmac_f32_e32 v133, v252, v189
	v_fmac_f32_e32 v149, v253, v189
	v_fmac_f32_e32 v134, v252, v190
	v_fmac_f32_e32 v150, v253, v190
	v_fmac_f32_e32 v135, v252, v191
	v_fmac_f32_e32 v151, v253, v191
	s_waitcnt lgkmcnt(5)
	v_fmac_f32_e32 v136, v252, v232
	v_fmac_f32_e32 v152, v253, v232
	v_fmac_f32_e32 v137, v252, v233
	v_fmac_f32_e32 v153, v253, v233
	v_fmac_f32_e32 v138, v252, v234
	v_fmac_f32_e32 v154, v253, v234
	v_fmac_f32_e32 v139, v252, v235
	v_fmac_f32_e32 v155, v253, v235
	s_waitcnt lgkmcnt(4)
	v_fmac_f32_e32 v140, v252, v240
	v_fmac_f32_e32 v156, v253, v240
	v_fmac_f32_e32 v141, v252, v241
	v_fmac_f32_e32 v157, v253, v241
	v_fmac_f32_e32 v142, v252, v242
	v_fmac_f32_e32 v158, v253, v242
	v_fmac_f32_e32 v143, v252, v243
	v_fmac_f32_e32 v159, v253, v243
	ds_read_b128 v[184:187], v248 offset:53248
	ds_read_b128 v[188:191], v249 offset:53248
	ds_read_b128 v[232:235], v250 offset:53248
	ds_read_b128 v[240:243], v251 offset:53248
	v_mul_f32_e32 v252, v28, v228
	v_fmac_f32_e32 v254, v28, v28
	v_mul_f32_e32 v253, v60, v228
	v_fmac_f32_e32 v255, v60, v60
	s_waitcnt lgkmcnt(7)
	v_fmac_f32_e32 v128, v252, v168
	v_fmac_f32_e32 v144, v253, v168
	v_fmac_f32_e32 v129, v252, v169
	v_fmac_f32_e32 v145, v253, v169
	v_fmac_f32_e32 v130, v252, v170
	v_fmac_f32_e32 v146, v253, v170
	v_fmac_f32_e32 v131, v252, v171
	v_fmac_f32_e32 v147, v253, v171
	s_waitcnt lgkmcnt(6)
	v_fmac_f32_e32 v132, v252, v172
	v_fmac_f32_e32 v148, v253, v172
	v_fmac_f32_e32 v133, v252, v173
	v_fmac_f32_e32 v149, v253, v173
	v_fmac_f32_e32 v134, v252, v174
	v_fmac_f32_e32 v150, v253, v174
	v_fmac_f32_e32 v135, v252, v175
	v_fmac_f32_e32 v151, v253, v175
	s_waitcnt lgkmcnt(5)
	v_fmac_f32_e32 v136, v252, v176
	v_fmac_f32_e32 v152, v253, v176
	v_fmac_f32_e32 v137, v252, v177
	v_fmac_f32_e32 v153, v253, v177
	v_fmac_f32_e32 v138, v252, v178
	v_fmac_f32_e32 v154, v253, v178
	v_fmac_f32_e32 v139, v252, v179
	v_fmac_f32_e32 v155, v253, v179
	s_waitcnt lgkmcnt(4)
	v_fmac_f32_e32 v140, v252, v180
	v_fmac_f32_e32 v156, v253, v180
	v_fmac_f32_e32 v141, v252, v181
	v_fmac_f32_e32 v157, v253, v181
	v_fmac_f32_e32 v142, v252, v182
	v_fmac_f32_e32 v158, v253, v182
	v_fmac_f32_e32 v143, v252, v183
	v_fmac_f32_e32 v159, v253, v183
	ds_read_b128 v[168:171], v248 offset:57344
	ds_read_b128 v[172:175], v249 offset:57344
	ds_read_b128 v[176:179], v250 offset:57344
	ds_read_b128 v[180:183], v251 offset:57344
	v_mul_f32_e32 v252, v29, v229
	v_fmac_f32_e32 v254, v29, v29
	v_mul_f32_e32 v253, v61, v229
	v_fmac_f32_e32 v255, v61, v61
	s_waitcnt lgkmcnt(7)
	v_fmac_f32_e32 v128, v252, v184
	v_fmac_f32_e32 v144, v253, v184
	v_fmac_f32_e32 v129, v252, v185
	v_fmac_f32_e32 v145, v253, v185
	v_fmac_f32_e32 v130, v252, v186
	v_fmac_f32_e32 v146, v253, v186
	v_fmac_f32_e32 v131, v252, v187
	v_fmac_f32_e32 v147, v253, v187
	s_waitcnt lgkmcnt(6)
	v_fmac_f32_e32 v132, v252, v188
	v_fmac_f32_e32 v148, v253, v188
	v_fmac_f32_e32 v133, v252, v189
	v_fmac_f32_e32 v149, v253, v189
	v_fmac_f32_e32 v134, v252, v190
	v_fmac_f32_e32 v150, v253, v190
	v_fmac_f32_e32 v135, v252, v191
	v_fmac_f32_e32 v151, v253, v191
	s_waitcnt lgkmcnt(5)
	v_fmac_f32_e32 v136, v252, v232
	v_fmac_f32_e32 v152, v253, v232
	v_fmac_f32_e32 v137, v252, v233
	v_fmac_f32_e32 v153, v253, v233
	v_fmac_f32_e32 v138, v252, v234
	v_fmac_f32_e32 v154, v253, v234
	v_fmac_f32_e32 v139, v252, v235
	v_fmac_f32_e32 v155, v253, v235
	s_waitcnt lgkmcnt(4)
	v_fmac_f32_e32 v140, v252, v240
	v_fmac_f32_e32 v156, v253, v240
	v_fmac_f32_e32 v141, v252, v241
	v_fmac_f32_e32 v157, v253, v241
	v_fmac_f32_e32 v142, v252, v242
	v_fmac_f32_e32 v158, v253, v242
	v_fmac_f32_e32 v143, v252, v243
	v_fmac_f32_e32 v159, v253, v243
	ds_read_b128 v[184:187], v248 offset:61440
	ds_read_b128 v[188:191], v249 offset:61440
	ds_read_b128 v[232:235], v250 offset:61440
	ds_read_b128 v[240:243], v251 offset:61440
	v_mul_f32_e32 v252, v30, v230
	v_fmac_f32_e32 v254, v30, v30
	v_mul_f32_e32 v253, v62, v230
	v_fmac_f32_e32 v255, v62, v62
	s_waitcnt lgkmcnt(7)
	v_fmac_f32_e32 v128, v252, v168
	v_fmac_f32_e32 v144, v253, v168
	v_fmac_f32_e32 v129, v252, v169
	v_fmac_f32_e32 v145, v253, v169
	v_fmac_f32_e32 v130, v252, v170
	v_fmac_f32_e32 v146, v253, v170
	v_fmac_f32_e32 v131, v252, v171
	v_fmac_f32_e32 v147, v253, v171
	s_waitcnt lgkmcnt(6)
	v_fmac_f32_e32 v132, v252, v172
	v_fmac_f32_e32 v148, v253, v172
	v_fmac_f32_e32 v133, v252, v173
	v_fmac_f32_e32 v149, v253, v173
	v_fmac_f32_e32 v134, v252, v174
	v_fmac_f32_e32 v150, v253, v174
	v_fmac_f32_e32 v135, v252, v175
	v_fmac_f32_e32 v151, v253, v175
	s_waitcnt lgkmcnt(5)
	v_fmac_f32_e32 v136, v252, v176
	v_fmac_f32_e32 v152, v253, v176
	v_fmac_f32_e32 v137, v252, v177
	v_fmac_f32_e32 v153, v253, v177
	v_fmac_f32_e32 v138, v252, v178
	v_fmac_f32_e32 v154, v253, v178
	v_fmac_f32_e32 v139, v252, v179
	v_fmac_f32_e32 v155, v253, v179
	s_waitcnt lgkmcnt(4)
	v_fmac_f32_e32 v140, v252, v180
	v_fmac_f32_e32 v156, v253, v180
	v_fmac_f32_e32 v141, v252, v181
	v_fmac_f32_e32 v157, v253, v181
	v_fmac_f32_e32 v142, v252, v182
	v_fmac_f32_e32 v158, v253, v182
	v_fmac_f32_e32 v143, v252, v183
	v_fmac_f32_e32 v159, v253, v183
	v_mul_f32_e32 v252, v31, v231
	v_fmac_f32_e32 v254, v31, v31
	v_mul_f32_e32 v253, v63, v231
	v_fmac_f32_e32 v255, v63, v63
	s_waitcnt lgkmcnt(3)
	v_fmac_f32_e32 v128, v252, v184
	v_fmac_f32_e32 v144, v253, v184
	v_fmac_f32_e32 v129, v252, v185
	v_fmac_f32_e32 v145, v253, v185
	v_fmac_f32_e32 v130, v252, v186
	v_fmac_f32_e32 v146, v253, v186
	v_fmac_f32_e32 v131, v252, v187
	v_fmac_f32_e32 v147, v253, v187
	s_waitcnt lgkmcnt(2)
	v_fmac_f32_e32 v132, v252, v188
	v_fmac_f32_e32 v148, v253, v188
	v_fmac_f32_e32 v133, v252, v189
	v_fmac_f32_e32 v149, v253, v189
	v_fmac_f32_e32 v134, v252, v190
	v_fmac_f32_e32 v150, v253, v190
	v_fmac_f32_e32 v135, v252, v191
	v_fmac_f32_e32 v151, v253, v191
	s_waitcnt lgkmcnt(1)
	v_fmac_f32_e32 v136, v252, v232
	v_fmac_f32_e32 v152, v253, v232
	v_fmac_f32_e32 v137, v252, v233
	v_fmac_f32_e32 v153, v253, v233
	v_fmac_f32_e32 v138, v252, v234
	v_fmac_f32_e32 v154, v253, v234
	v_fmac_f32_e32 v139, v252, v235
	v_fmac_f32_e32 v155, v253, v235
	s_waitcnt lgkmcnt(0)
	v_fmac_f32_e32 v140, v252, v240
	v_fmac_f32_e32 v156, v253, v240
	v_fmac_f32_e32 v141, v252, v241
	v_fmac_f32_e32 v157, v253, v241
	v_fmac_f32_e32 v142, v252, v242
	v_fmac_f32_e32 v158, v253, v242
	v_fmac_f32_e32 v143, v252, v243
	v_fmac_f32_e32 v159, v253, v243
	v_xor_b32_e32 v162, 32, v197
	v_lshlrev_b32_e32 v162, 2, v162
	ds_bpermute_b32 v160, v162, v254
	ds_bpermute_b32 v161, v162, v255
	s_waitcnt lgkmcnt(0)
	v_add_f32_e32 v254, v254, v160
	v_add_f32_e32 v255, v255, v161
	v_xor_b32_e32 v162, 16, v197
	v_lshlrev_b32_e32 v162, 2, v162
	ds_bpermute_b32 v160, v162, v254
	ds_bpermute_b32 v161, v162, v255
	s_waitcnt lgkmcnt(0)
	v_add_f32_e32 v254, v254, v160
	v_add_f32_e32 v255, v255, v161
	v_xor_b32_e32 v162, 8, v197
	v_lshlrev_b32_e32 v162, 2, v162
	ds_bpermute_b32 v160, v162, v254
	ds_bpermute_b32 v161, v162, v255
	s_waitcnt lgkmcnt(0)
	v_add_f32_e32 v254, v254, v160
	v_add_f32_e32 v255, v255, v161
	v_xor_b32_e32 v162, 4, v197
	v_lshlrev_b32_e32 v162, 2, v162
	ds_bpermute_b32 v160, v162, v254
	ds_bpermute_b32 v161, v162, v255
	s_waitcnt lgkmcnt(0)
	v_add_f32_e32 v254, v254, v160
	v_add_f32_e32 v255, v255, v161
	v_xor_b32_e32 v162, 2, v197
	v_lshlrev_b32_e32 v162, 2, v162
	ds_bpermute_b32 v160, v162, v254
	ds_bpermute_b32 v161, v162, v255
	s_waitcnt lgkmcnt(0)
	v_add_f32_e32 v254, v254, v160
	v_add_f32_e32 v255, v255, v161
	v_xor_b32_e32 v162, 1, v197
	v_lshlrev_b32_e32 v162, 2, v162
	ds_bpermute_b32 v160, v162, v254
	ds_bpermute_b32 v161, v162, v255
	s_waitcnt lgkmcnt(0)
	v_add_f32_e32 v254, v254, v160
	v_add_f32_e32 v255, v255, v161
	v_mov_b32_e32 v160, 0x358637bd
	v_fma_f32 v254, v254, s20, v160
	v_fma_f32 v255, v255, s20, v160
	v_rsq_f32_e32 v254, v254
	v_rsq_f32_e32 v255, v255
	s_nop 0
	s_lshl_b32 s18, s16, 12
	s_add_u32 s22, s6, s18
	s_addc_u32 s23, s7, 0
	v_mul_f32_e32 v163, v0, v254
	v_mul_f32_e32 v165, v1, v254
	v_mul_f32_e32 v167, v2, v254
	v_mul_f32_e32 v199, v3, v254
	v_mul_f32_e32 v163, v163, v200
	v_mul_f32_e32 v165, v165, v201
	v_mul_f32_e32 v167, v167, v202
	v_mul_f32_e32 v199, v199, v203
	v_cvt_pk_bf16_f32 v192, v163, v165
	v_cvt_pk_bf16_f32 v193, v167, v199
	global_store_dwordx2 v164, v[192:193], s[22:23] offset:0
	v_mul_f32_e32 v163, v4, v254
	v_mul_f32_e32 v165, v5, v254
	v_mul_f32_e32 v167, v6, v254
	v_mul_f32_e32 v199, v7, v254
	v_mul_f32_e32 v163, v163, v204
	v_mul_f32_e32 v165, v165, v205
	v_mul_f32_e32 v167, v167, v206
	v_mul_f32_e32 v199, v199, v207
	v_cvt_pk_bf16_f32 v238, v163, v165
	v_cvt_pk_bf16_f32 v239, v167, v199
	global_store_dwordx2 v164, v[238:239], s[22:23] offset:512
	v_mul_f32_e32 v163, v8, v254
	v_mul_f32_e32 v165, v9, v254
	v_mul_f32_e32 v167, v10, v254
	v_mul_f32_e32 v199, v11, v254
	v_mul_f32_e32 v163, v163, v208
	v_mul_f32_e32 v165, v165, v209
	v_mul_f32_e32 v167, v167, v210
	v_mul_f32_e32 v199, v199, v211
	v_cvt_pk_bf16_f32 v192, v163, v165
	v_cvt_pk_bf16_f32 v193, v167, v199
	global_store_dwordx2 v164, v[192:193], s[22:23] offset:1024
	v_mul_f32_e32 v163, v12, v254
	v_mul_f32_e32 v165, v13, v254
	v_mul_f32_e32 v167, v14, v254
	v_mul_f32_e32 v199, v15, v254
	v_mul_f32_e32 v163, v163, v212
	v_mul_f32_e32 v165, v165, v213
	v_mul_f32_e32 v167, v167, v214
	v_mul_f32_e32 v199, v199, v215
	v_cvt_pk_bf16_f32 v238, v163, v165
	v_cvt_pk_bf16_f32 v239, v167, v199
	global_store_dwordx2 v164, v[238:239], s[22:23] offset:1536
	v_mul_f32_e32 v163, v16, v254
	v_mul_f32_e32 v165, v17, v254
	v_mul_f32_e32 v167, v18, v254
	v_mul_f32_e32 v199, v19, v254
	v_mul_f32_e32 v163, v163, v216
	v_mul_f32_e32 v165, v165, v217
	v_mul_f32_e32 v167, v167, v218
	v_mul_f32_e32 v199, v199, v219
	v_cvt_pk_bf16_f32 v192, v163, v165
	v_cvt_pk_bf16_f32 v193, v167, v199
	global_store_dwordx2 v164, v[192:193], s[22:23] offset:2048
	v_mul_f32_e32 v163, v20, v254
	v_mul_f32_e32 v165, v21, v254
	v_mul_f32_e32 v167, v22, v254
	v_mul_f32_e32 v199, v23, v254
	v_mul_f32_e32 v163, v163, v220
	v_mul_f32_e32 v165, v165, v221
	v_mul_f32_e32 v167, v167, v222
	v_mul_f32_e32 v199, v199, v223
	v_cvt_pk_bf16_f32 v238, v163, v165
	v_cvt_pk_bf16_f32 v239, v167, v199
	global_store_dwordx2 v164, v[238:239], s[22:23] offset:2560
	v_mul_f32_e32 v163, v24, v254
	v_mul_f32_e32 v165, v25, v254
	v_mul_f32_e32 v167, v26, v254
	v_mul_f32_e32 v199, v27, v254
	v_mul_f32_e32 v163, v163, v224
	v_mul_f32_e32 v165, v165, v225
	v_mul_f32_e32 v167, v167, v226
	v_mul_f32_e32 v199, v199, v227
	v_cvt_pk_bf16_f32 v192, v163, v165
	v_cvt_pk_bf16_f32 v193, v167, v199
	global_store_dwordx2 v164, v[192:193], s[22:23] offset:3072
	v_mul_f32_e32 v163, v28, v254
	v_mul_f32_e32 v165, v29, v254
	v_mul_f32_e32 v167, v30, v254
	v_mul_f32_e32 v199, v31, v254
	v_mul_f32_e32 v163, v163, v228
	v_mul_f32_e32 v165, v165, v229
	v_mul_f32_e32 v167, v167, v230
	v_mul_f32_e32 v199, v199, v231
	v_cvt_pk_bf16_f32 v238, v163, v165
	v_cvt_pk_bf16_f32 v239, v167, v199
	global_store_dwordx2 v164, v[238:239], s[22:23] offset:3584
	s_add_u32 s22, s22, 0x1000
	s_addc_u32 s23, s23, 0
	v_mul_f32_e32 v163, v32, v255
	v_mul_f32_e32 v165, v33, v255
	v_mul_f32_e32 v167, v34, v255
	v_mul_f32_e32 v199, v35, v255
	v_mul_f32_e32 v163, v163, v200
	v_mul_f32_e32 v165, v165, v201
	v_mul_f32_e32 v167, v167, v202
	v_mul_f32_e32 v199, v199, v203
	v_cvt_pk_bf16_f32 v192, v163, v165
	v_cvt_pk_bf16_f32 v193, v167, v199
	global_store_dwordx2 v164, v[192:193], s[22:23] offset:0
	v_mul_f32_e32 v163, v36, v255
	v_mul_f32_e32 v165, v37, v255
	v_mul_f32_e32 v167, v38, v255
	v_mul_f32_e32 v199, v39, v255
	v_mul_f32_e32 v163, v163, v204
	v_mul_f32_e32 v165, v165, v205
	v_mul_f32_e32 v167, v167, v206
	v_mul_f32_e32 v199, v199, v207
	v_cvt_pk_bf16_f32 v238, v163, v165
	v_cvt_pk_bf16_f32 v239, v167, v199
	global_store_dwordx2 v164, v[238:239], s[22:23] offset:512
	v_mul_f32_e32 v163, v40, v255
	v_mul_f32_e32 v165, v41, v255
	v_mul_f32_e32 v167, v42, v255
	v_mul_f32_e32 v199, v43, v255
	v_mul_f32_e32 v163, v163, v208
	v_mul_f32_e32 v165, v165, v209
	v_mul_f32_e32 v167, v167, v210
	v_mul_f32_e32 v199, v199, v211
	v_cvt_pk_bf16_f32 v192, v163, v165
	v_cvt_pk_bf16_f32 v193, v167, v199
	global_store_dwordx2 v164, v[192:193], s[22:23] offset:1024
	v_mul_f32_e32 v163, v44, v255
	v_mul_f32_e32 v165, v45, v255
	v_mul_f32_e32 v167, v46, v255
	v_mul_f32_e32 v199, v47, v255
	v_mul_f32_e32 v163, v163, v212
	v_mul_f32_e32 v165, v165, v213
	v_mul_f32_e32 v167, v167, v214
	v_mul_f32_e32 v199, v199, v215
	v_cvt_pk_bf16_f32 v238, v163, v165
	v_cvt_pk_bf16_f32 v239, v167, v199
	global_store_dwordx2 v164, v[238:239], s[22:23] offset:1536
	v_mul_f32_e32 v163, v48, v255
	v_mul_f32_e32 v165, v49, v255
	v_mul_f32_e32 v167, v50, v255
	v_mul_f32_e32 v199, v51, v255
	v_mul_f32_e32 v163, v163, v216
	v_mul_f32_e32 v165, v165, v217
	v_mul_f32_e32 v167, v167, v218
	v_mul_f32_e32 v199, v199, v219
	v_cvt_pk_bf16_f32 v192, v163, v165
	v_cvt_pk_bf16_f32 v193, v167, v199
	global_store_dwordx2 v164, v[192:193], s[22:23] offset:2048
	v_mul_f32_e32 v163, v52, v255
	v_mul_f32_e32 v165, v53, v255
	v_mul_f32_e32 v167, v54, v255
	v_mul_f32_e32 v199, v55, v255
	v_mul_f32_e32 v163, v163, v220
	v_mul_f32_e32 v165, v165, v221
	v_mul_f32_e32 v167, v167, v222
	v_mul_f32_e32 v199, v199, v223
	v_cvt_pk_bf16_f32 v238, v163, v165
	v_cvt_pk_bf16_f32 v239, v167, v199
	global_store_dwordx2 v164, v[238:239], s[22:23] offset:2560
	v_mul_f32_e32 v163, v56, v255
	v_mul_f32_e32 v165, v57, v255
	v_mul_f32_e32 v167, v58, v255
	v_mul_f32_e32 v199, v59, v255
	v_mul_f32_e32 v163, v163, v224
	v_mul_f32_e32 v165, v165, v225
	v_mul_f32_e32 v167, v167, v226
	v_mul_f32_e32 v199, v199, v227
	v_cvt_pk_bf16_f32 v192, v163, v165
	v_cvt_pk_bf16_f32 v193, v167, v199
	global_store_dwordx2 v164, v[192:193], s[22:23] offset:3072
	v_mul_f32_e32 v163, v60, v255
	v_mul_f32_e32 v165, v61, v255
	v_mul_f32_e32 v167, v62, v255
	v_mul_f32_e32 v199, v63, v255
	v_mul_f32_e32 v163, v163, v228
	v_mul_f32_e32 v165, v165, v229
	v_mul_f32_e32 v167, v167, v230
	v_mul_f32_e32 v199, v199, v231
	v_cvt_pk_bf16_f32 v238, v163, v165
	v_cvt_pk_bf16_f32 v239, v167, v199
	global_store_dwordx2 v164, v[238:239], s[22:23] offset:3584
	v_xor_b32_e32 v162, 32, v197
	v_lshlrev_b32_e32 v162, 2, v162
	v_cndmask_b32_e64 v163, v144, v128, s[24:25]
	v_cndmask_b32_e64 v128, v128, v144, s[24:25]
	ds_bpermute_b32 v144, v162, v163
	v_cndmask_b32_e64 v165, v145, v129, s[24:25]
	v_cndmask_b32_e64 v129, v129, v145, s[24:25]
	ds_bpermute_b32 v145, v162, v165
	v_cndmask_b32_e64 v167, v146, v130, s[24:25]
	v_cndmask_b32_e64 v130, v130, v146, s[24:25]
	ds_bpermute_b32 v146, v162, v167
	v_cndmask_b32_e64 v199, v147, v131, s[24:25]
	v_cndmask_b32_e64 v131, v131, v147, s[24:25]
	ds_bpermute_b32 v147, v162, v199
	v_cndmask_b32_e64 v163, v148, v132, s[24:25]
	v_cndmask_b32_e64 v132, v132, v148, s[24:25]
	ds_bpermute_b32 v148, v162, v163
	v_cndmask_b32_e64 v165, v149, v133, s[24:25]
	v_cndmask_b32_e64 v133, v133, v149, s[24:25]
	ds_bpermute_b32 v149, v162, v165
	v_cndmask_b32_e64 v167, v150, v134, s[24:25]
	v_cndmask_b32_e64 v134, v134, v150, s[24:25]
	ds_bpermute_b32 v150, v162, v167
	v_cndmask_b32_e64 v199, v151, v135, s[24:25]
	v_cndmask_b32_e64 v135, v135, v151, s[24:25]
	ds_bpermute_b32 v151, v162, v199
	s_waitcnt lgkmcnt(0)
	v_add_f32_e32 v128, v128, v144
	v_add_f32_e32 v129, v129, v145
	v_add_f32_e32 v130, v130, v146
	v_add_f32_e32 v131, v131, v147
	v_add_f32_e32 v132, v132, v148
	v_add_f32_e32 v133, v133, v149
	v_add_f32_e32 v134, v134, v150
	v_add_f32_e32 v135, v135, v151
	v_cndmask_b32_e64 v163, v152, v136, s[24:25]
	v_cndmask_b32_e64 v136, v136, v152, s[24:25]
	ds_bpermute_b32 v152, v162, v163
	v_cndmask_b32_e64 v165, v153, v137, s[24:25]
	v_cndmask_b32_e64 v137, v137, v153, s[24:25]
	ds_bpermute_b32 v153, v162, v165
	v_cndmask_b32_e64 v167, v154, v138, s[24:25]
	v_cndmask_b32_e64 v138, v138, v154, s[24:25]
	ds_bpermute_b32 v154, v162, v167
	v_cndmask_b32_e64 v199, v155, v139, s[24:25]
	v_cndmask_b32_e64 v139, v139, v155, s[24:25]
	ds_bpermute_b32 v155, v162, v199
	v_cndmask_b32_e64 v163, v156, v140, s[24:25]
	v_cndmask_b32_e64 v140, v140, v156, s[24:25]
	ds_bpermute_b32 v156, v162, v163
	v_cndmask_b32_e64 v165, v157, v141, s[24:25]
	v_cndmask_b32_e64 v141, v141, v157, s[24:25]
	ds_bpermute_b32 v157, v162, v165
	v_cndmask_b32_e64 v167, v158, v142, s[24:25]
	v_cndmask_b32_e64 v142, v142, v158, s[24:25]
	ds_bpermute_b32 v158, v162, v167
	v_cndmask_b32_e64 v199, v159, v143, s[24:25]
	v_cndmask_b32_e64 v143, v143, v159, s[24:25]
	ds_bpermute_b32 v159, v162, v199
	s_waitcnt lgkmcnt(0)
	v_add_f32_e32 v136, v136, v152
	v_add_f32_e32 v137, v137, v153
	v_add_f32_e32 v138, v138, v154
	v_add_f32_e32 v139, v139, v155
	v_add_f32_e32 v140, v140, v156
	v_add_f32_e32 v141, v141, v157
	v_add_f32_e32 v142, v142, v158
	v_add_f32_e32 v143, v143, v159
	v_xor_b32_e32 v162, 16, v197
	v_lshlrev_b32_e32 v162, 2, v162
	v_cndmask_b32_e64 v163, v136, v128, s[26:27]
	v_cndmask_b32_e64 v128, v128, v136, s[26:27]
	ds_bpermute_b32 v136, v162, v163
	v_cndmask_b32_e64 v165, v137, v129, s[26:27]
	v_cndmask_b32_e64 v129, v129, v137, s[26:27]
	ds_bpermute_b32 v137, v162, v165
	v_cndmask_b32_e64 v167, v138, v130, s[26:27]
	v_cndmask_b32_e64 v130, v130, v138, s[26:27]
	ds_bpermute_b32 v138, v162, v167
	v_cndmask_b32_e64 v199, v139, v131, s[26:27]
	v_cndmask_b32_e64 v131, v131, v139, s[26:27]
	ds_bpermute_b32 v139, v162, v199
	v_cndmask_b32_e64 v163, v140, v132, s[26:27]
	v_cndmask_b32_e64 v132, v132, v140, s[26:27]
	ds_bpermute_b32 v140, v162, v163
	v_cndmask_b32_e64 v165, v141, v133, s[26:27]
	v_cndmask_b32_e64 v133, v133, v141, s[26:27]
	ds_bpermute_b32 v141, v162, v165
	v_cndmask_b32_e64 v167, v142, v134, s[26:27]
	v_cndmask_b32_e64 v134, v134, v142, s[26:27]
	ds_bpermute_b32 v142, v162, v167
	v_cndmask_b32_e64 v199, v143, v135, s[26:27]
	v_cndmask_b32_e64 v135, v135, v143, s[26:27]
	ds_bpermute_b32 v143, v162, v199
	s_waitcnt lgkmcnt(0)
	v_add_f32_e32 v128, v128, v136
	v_add_f32_e32 v129, v129, v137
	v_add_f32_e32 v130, v130, v138
	v_add_f32_e32 v131, v131, v139
	v_add_f32_e32 v132, v132, v140
	v_add_f32_e32 v133, v133, v141
	v_add_f32_e32 v134, v134, v142
	v_add_f32_e32 v135, v135, v143
	v_xor_b32_e32 v162, 8, v197
	v_lshlrev_b32_e32 v162, 2, v162
	v_cndmask_b32_e64 v163, v132, v128, s[28:29]
	v_cndmask_b32_e64 v128, v128, v132, s[28:29]
	ds_bpermute_b32 v132, v162, v163
	v_cndmask_b32_e64 v165, v133, v129, s[28:29]
	v_cndmask_b32_e64 v129, v129, v133, s[28:29]
	ds_bpermute_b32 v133, v162, v165
	v_cndmask_b32_e64 v167, v134, v130, s[28:29]
	v_cndmask_b32_e64 v130, v130, v134, s[28:29]
	ds_bpermute_b32 v134, v162, v167
	v_cndmask_b32_e64 v199, v135, v131, s[28:29]
	v_cndmask_b32_e64 v131, v131, v135, s[28:29]
	ds_bpermute_b32 v135, v162, v199
	s_waitcnt lgkmcnt(0)
	v_add_f32_e32 v128, v128, v132
	v_add_f32_e32 v129, v129, v133
	v_add_f32_e32 v130, v130, v134
	v_add_f32_e32 v131, v131, v135
	v_xor_b32_e32 v162, 4, v197
	v_lshlrev_b32_e32 v162, 2, v162
	v_cndmask_b32_e64 v163, v130, v128, s[30:31]
	v_cndmask_b32_e64 v128, v128, v130, s[30:31]
	ds_bpermute_b32 v130, v162, v163
	v_cndmask_b32_e64 v165, v131, v129, s[30:31]
	v_cndmask_b32_e64 v129, v129, v131, s[30:31]
	ds_bpermute_b32 v131, v162, v165
	s_waitcnt lgkmcnt(0)
	v_add_f32_e32 v128, v128, v130
	v_add_f32_e32 v129, v129, v131
	v_xor_b32_e32 v162, 2, v197
	v_lshlrev_b32_e32 v162, 2, v162
	v_cndmask_b32_e64 v163, v129, v128, s[34:35]
	v_cndmask_b32_e64 v128, v128, v129, s[34:35]
	ds_bpermute_b32 v129, v162, v163
	s_waitcnt lgkmcnt(0)
	v_add_f32_e32 v128, v128, v129
	v_xor_b32_e32 v162, 1, v197
	v_lshlrev_b32_e32 v162, 2, v162
	ds_bpermute_b32 v160, v162, v128
	s_waitcnt lgkmcnt(0)
	v_add_f32_e32 v128, v128, v160
	v_cndmask_b32_e64 v160, v254, v255, s[24:25]
	v_mul_f32_e32 v128, v128, v160
	v_mul_f32_e32 v163, 0xbfb8aa3b, v128
	v_exp_f32_e32 v163, v163
	v_add_f32_e32 v167, v128, v195
	v_add_f32_e32 v163, 1.0, v163
	v_and_b32_e32 v199, 0x7fffffff, v167
	v_mul_f32_e32 v199, 0xbfb8aa3b, v199
	v_exp_f32_e32 v199, v199
	v_rcp_f32_e32 v163, v163
	v_add_f32_e32 v160, 1.0, v199
	v_log_f32_e32 v160, v160
	v_mul_f32_e32 v161, v199, v199
	v_mul_f32_e32 v160, 0x3f317218, v160
	v_mul_f32_e32 v162, v161, v199
	v_fma_f32 v161, v161, -0.5, v199
	v_mov_b32_e32 v165, 0x3eaaaaab
	v_fmac_f32_e32 v161, v162, v165
	v_cmp_gt_f32_e32 vcc, 0x3c800000, v199
	v_max_f32_e32 v167, 0, v167
	s_nop 0
	v_cndmask_b32_e32 v160, v160, v161, vcc
	v_add_f32_e32 v167, v167, v160
	v_mul_f32_e64 v165, -v237, v167
	v_bfe_u32 v162, v197, 1, 4
	v_cmp_gt_u32_e32 vcc, 8, v162
	v_and_b32_e32 v162, 7, v162
	s_lshr_b32 s18, s16, 11
	s_lshl_b32 s18, s18, 3
	v_add_u32_e32 v162, s18, v162
	v_lshlrev_b32_e32 v162, 13, v162
	s_and_b32 s18, s16, 2047
	v_lshrrev_b32_e32 v161, 5, v197
	v_add_u32_e32 v161, s18, v161
	v_lshl_add_u32 v162, v161, 2, v162
	v_cndmask_b32_e32 v160, v165, v163, vcc
	v_and_b32_e32 v161, 1, v197
	v_cmp_eq_u32_e64 s[22:23], 0, v161
	s_nop 1
	s_and_b64 s[0:1], s[22:23], vcc
	s_andn2_b64 s[2:3], s[22:23], vcc
	s_mov_b64 s[22:23], exec
	s_mov_b64 exec, s[0:1]
	global_store_dword v162, v160, s[12:13]
	s_mov_b64 exec, s[2:3]
	global_store_dword v162, v160, s[14:15]
	s_mov_b64 exec, s[22:23]
	s_add_u32 s16, s16, 2
	s_add_u32 s17, s17, 1
	s_cmp_lt_u32 s17, 4
	s_cbranch_scc1 .Lp0_loop
	v_lshrrev_b32_e32 v136, 4, v198
	v_lshrrev_b32_e32 v145, 3, v198
	v_lshlrev_b32_e32 v144, 3, v198
	v_readlane_b32 s72, v236, 22
	v_readlane_b32 s73, v236, 23
	v_readlane_b32 s74, v236, 24
	v_readlane_b32 s75, v236, 25
	v_readlane_b32 s76, v236, 26
	v_readlane_b32 s77, v236, 27
	v_readlane_b32 s78, v236, 28
	v_readlane_b32 s79, v236, 29
	v_readlane_b32 s80, v236, 30
	v_readlane_b32 s81, v236, 31
	v_readlane_b32 s82, v236, 32
	v_readlane_b32 s83, v236, 33
	v_readlane_b32 s84, v236, 34
	v_readlane_b32 s85, v236, 35
	v_readlane_b32 s86, v236, 36
	v_readlane_b32 s87, v236, 37
	s_nop 3
